# phase 0 rows loop: gate-weight LDS reads issued 8 reads ahead into free registers with counted lgkmcnt waits
# speedup vs baseline: 1.0104x; 1.0083x over previous
; #define LAS __attribute__((address_space(3)))
; __device__ __forceinline__ unsigned cvt_pk_bf16(float lo, float hi) { unsigned r; asm volatile("v_cvt_pk_bf16_f32 %0, %1, %2" : "=v"(r) : "v"(lo), "v"(hi)); return r; }
; __device__ void phase0(const Params& P, LAS unsigned char* lds, const int G, const int bid) {
;     ...
;       for (int row0 = bid * 8 + wid; row0 < NTOK; row0 += G * 8 * 4) {
;           f32x4 vv[4][4];
; #pragma unroll
;           for (int rr = 0; rr < 4; ++rr) { const int row = row0 + rr * G * 8; const float* xr = xrow(P, row < NTOK ? row : row0);
; #pragma unroll
;               for (int i = 0; i < 4; ++i) vv[rr][i] = __builtin_nontemporal_load((const f32x4*)(xr + 4 * lane + 256 * i)); }
; #pragma unroll
;           for (int rr = 0; rr < 4; ++rr) { const int row = row0 + rr * G * 8; if (row >= NTOK) continue;
;               f32x4 (&v)[4] = vv[rr]; float ss = 0.f;
; #pragma unroll
;               for (int i = 0; i < 4; ++i)
; #pragma unroll
;                   for (int j = 0; j < 4; ++j) ss += v[i][j] * v[i][j];
; #pragma unroll
;               for (int o = 32; o >= 1; o >>= 1) ss += __shfl_xor(ss, o);
;               const float rstd = rsqrtf(ss * (1.0f / DM) + 1e-6f);
;               float ga[16];
; #pragma unroll
;               for (int c = 0; c < 16; ++c) ga[c] = 0.f;
; #pragma unroll
;               for (int i = 0; i < 4; ++i) { v[i] = v[i] * rstd * w4[i];
;                   u32x2 w; w.x = cvt_pk_bf16(v[i][0], v[i][1]); w.y = cvt_pk_bf16(v[i][2], v[i][3]);
;                   *(u32x2*)(abf + (size_t)row * DM + 4 * lane + 256 * i) = w;
; #pragma unroll
;                   for (int j = 0; j < 4; ++j) { const LAS float* wr_ = wg + (j * 256 + i * 64 + lane) * 20; const float a = v[i][j];
.LBB0_1046:
	v_readlane_b32 s60, v254, 34
	v_ashrrev_i32_e32 v89, 31, v88
	v_readlane_b32 s61, v254, 35
	v_readlane_b32 s62, v254, 36
	v_readlane_b32 s63, v254, 37
	v_cmp_gt_i32_e64 s[50:51], s14, v88
	s_waitcnt vmcnt(4)
	v_add_u32_e32 v20, 0xffffc000, v88
	v_mov_b32_e32 v28, s63
	v_mov_b32_e32 v29, s61
	v_mov_b32_e32 v30, s62
	v_mov_b32_e32 v31, s60
	v_cndmask_b32_e64 v21, 0, v89, s[50:51]
	v_cndmask_b32_e64 v20, v20, v88, s[50:51]
	s_waitcnt lgkmcnt(0)
	v_cndmask_b32_e64 v19, v28, v29, s[50:51]
	v_cndmask_b32_e64 v18, v30, v31, s[50:51]
	v_lshlrev_b64 v[20:21], 12, v[20:21]
	v_lshl_add_u64 v[18:19], v[18:19], 0, v[20:21]
	v_lshl_add_u64 v[18:19], v[18:19], 0, v[0:1]
	global_load_dwordx4 v[92:95], v[18:19], off nt
	global_load_dwordx4 v[66:69], v[18:19], off offset:3072 nt
	global_load_dwordx4 v[74:77], v[18:19], off offset:1024 nt
	global_load_dwordx4 v[70:73], v[18:19], off offset:2048 nt
	v_add_u32_e32 v82, s0, v88
	v_add_u32_e32 v86, s10, v88
	v_cmp_gt_i32_e64 s[50:51], s15, v82
	v_add_u32_e32 v84, s11, v88
	v_readlane_b32 s64, v254, 38
	v_cndmask_b32_e64 v18, v88, v82, s[50:51]
	v_cmp_gt_i32_e64 s[50:51], s15, v86
	v_add_u32_e32 v20, 0xffffc000, v18
	v_ashrrev_i32_e32 v19, 31, v18
	v_cndmask_b32_e64 v22, v88, v86, s[50:51]
	v_cmp_gt_i32_e64 s[50:51], s15, v84
	v_add_u32_e32 v24, 0xffffc000, v22
	v_ashrrev_i32_e32 v23, 31, v22
	v_cndmask_b32_e64 v32, v88, v84, s[50:51]
	v_cmp_gt_i32_e64 s[50:51], s14, v18
	v_ashrrev_i32_e32 v34, 31, v32
	v_add_u32_e32 v33, 0xffffc000, v32
	v_cndmask_b32_e64 v19, 0, v19, s[50:51]
	v_cndmask_b32_e64 v18, v20, v18, s[50:51]
	v_cndmask_b32_e64 v21, v28, v29, s[50:51]
	v_cndmask_b32_e64 v20, v30, v31, s[50:51]
	v_cmp_gt_i32_e64 s[50:51], s14, v22
	v_lshlrev_b64 v[18:19], 12, v[18:19]
	v_lshl_add_u64 v[18:19], v[20:21], 0, v[18:19]
	v_cndmask_b32_e64 v22, v24, v22, s[50:51]
	v_cndmask_b32_e64 v23, 0, v23, s[50:51]
	v_lshlrev_b64 v[22:23], 12, v[22:23]
	v_lshl_add_u64 v[18:19], v[18:19], 0, v[0:1]
	global_load_dwordx4 v[62:65], v[18:19], off nt
	global_load_dwordx4 v[58:61], v[18:19], off offset:1024 nt
	global_load_dwordx4 v[54:57], v[18:19], off offset:2048 nt
	global_load_dwordx4 v[50:53], v[18:19], off offset:3072 nt
	v_readlane_b32 s65, v254, 39
	v_readlane_b32 s66, v254, 40
	v_readlane_b32 s67, v254, 41
	v_readlane_b32 s68, v254, 42
	v_readlane_b32 s69, v254, 43
	v_readlane_b32 s70, v254, 44
	v_readlane_b32 s71, v254, 45
	v_readlane_b32 s72, v254, 46
	v_readlane_b32 s73, v254, 47
	v_readlane_b32 s74, v254, 48
	v_readlane_b32 s75, v254, 49
	s_waitcnt vmcnt(7)
	v_mul_f32_e32 v35, v93, v93
	v_fmac_f32_e32 v35, v92, v92
	v_fmac_f32_e32 v35, v94, v94
	v_fmac_f32_e32 v35, v95, v95
	s_waitcnt vmcnt(5)
	v_fmac_f32_e32 v35, v74, v74
	v_fmac_f32_e32 v35, v75, v75
	v_fmac_f32_e32 v35, v76, v76
	v_fmac_f32_e32 v35, v77, v77
	s_waitcnt vmcnt(4)
	v_fmac_f32_e32 v35, v70, v70
	v_fmac_f32_e32 v35, v71, v71
	v_fmac_f32_e32 v35, v72, v72
	v_pk_mul_f32 v[26:27], v[66:67], v[66:67]
	v_fmac_f32_e32 v35, v73, v73
	v_add_f32_e32 v26, v26, v35
	v_pk_mul_f32 v[24:25], v[68:69], v[68:69]
	v_add_f32_e32 v26, v27, v26
	v_add_f32_e32 v24, v24, v26
	v_add_f32_e32 v26, v25, v24
	ds_bpermute_b32 v35, v96, v26
	v_cndmask_b32_e64 v25, v28, v29, s[50:51]
	v_cndmask_b32_e64 v24, v30, v31, s[50:51]
	v_cmp_gt_i32_e64 s[50:51], s14, v32
	v_lshl_add_u64 v[20:21], v[24:25], 0, v[22:23]
	v_lshl_add_u64 v[20:21], v[20:21], 0, v[0:1]
	v_cndmask_b32_e64 v27, 0, v34, s[50:51]
	s_waitcnt lgkmcnt(0)
	v_add_f32_e32 v34, v26, v35
	ds_bpermute_b32 v35, v97, v34
	v_cndmask_b32_e64 v29, v28, v29, s[50:51]
	v_cndmask_b32_e64 v28, v30, v31, s[50:51]
	v_cndmask_b32_e64 v26, v33, v32, s[50:51]
	v_lshlrev_b64 v[26:27], 12, v[26:27]
	s_waitcnt lgkmcnt(0)
	v_add_f32_e32 v30, v34, v35
	ds_bpermute_b32 v31, v98, v30
	v_lshl_add_u64 v[22:23], v[28:29], 0, v[26:27]
	v_lshl_add_u64 v[116:117], v[22:23], 0, v[0:1]
	global_load_dwordx4 v[46:49], v[20:21], off nt
	global_load_dwordx4 v[42:45], v[20:21], off offset:1024 nt
	global_load_dwordx4 v[38:41], v[20:21], off offset:2048 nt
	global_load_dwordx4 v[34:37], v[20:21], off offset:3072 nt
	s_waitcnt lgkmcnt(0)
	v_add_f32_e32 v24, v30, v31
	ds_bpermute_b32 v25, v99, v24
	s_waitcnt lgkmcnt(0)
	v_add_f32_e32 v22, v24, v25
	ds_bpermute_b32 v23, v100, v22
	s_waitcnt lgkmcnt(0)
	v_add_f32_e32 v18, v22, v23
	ds_bpermute_b32 v19, v101, v18
	s_waitcnt lgkmcnt(0)
	v_add_f32_e32 v18, v18, v19
	v_fmamk_f32 v18, v18, 0x3a800000, v210
	v_mul_f32_e32 v19, 0x4b800000, v18
	v_cmp_gt_f32_e64 s[50:51], s30, v18
	s_nop 1
	v_cndmask_b32_e64 v18, v18, v19, s[50:51]
	v_rsq_f32_e32 v83, v18
	global_load_dwordx4 v[30:33], v[116:117], off nt
	global_load_dwordx4 v[26:29], v[116:117], off offset:1024 nt
	global_load_dwordx4 v[22:25], v[116:117], off offset:2048 nt
	global_load_dwordx4 v[18:21], v[116:117], off offset:3072 nt
	v_mul_f32_e32 v85, 0x45800000, v83
	v_cndmask_b32_e64 v90, v83, v85, s[50:51]
	v_pk_mul_f32 v[116:117], v[92:93], v[90:91] op_sel_hi:[1,0]
	v_pk_mul_f32 v[92:93], v[94:95], v[90:91] op_sel_hi:[1,0]
	v_pk_mul_f32 v[138:139], v[2:3], v[116:117]
	v_pk_mul_f32 v[92:93], v[4:5], v[92:93]
	v_cvt_pk_bf16_f32 v94, v138, v139
	v_pk_mul_f32 v[74:75], v[74:75], v[90:91] op_sel_hi:[1,0]
	v_cvt_pk_bf16_f32 v95, v92, v93
	ds_read_b128 v[140:143], v102 offset:40960
	ds_read_b128 v[144:147], v102 offset:40976
	ds_read_b128 v[148:151], v102 offset:61440
	ds_read_b128 v[152:155], v102 offset:61456
	ds_read_b128 v[156:159], v102 offset:40992
	ds_read_b128 v[170:173], v102 offset:41008
	ds_read_b128 v[174:177], v102 offset:61472
	ds_read_b128 v[178:181], v102 offset:61488
	ds_read_b128 v[182:185], v103 offset:40960
	ds_read_b128 v[188:191], v103 offset:40976
	ds_read_b128 v[192:195], v103 offset:40992
	ds_read_b128 v[196:199], v103 offset:41008
	v_pk_mul_f32 v[76:77], v[76:77], v[90:91] op_sel_hi:[1,0]
	v_pk_mul_f32 v[70:71], v[70:71], v[90:91] op_sel_hi:[1,0]
	s_waitcnt lgkmcnt(11)
; #define LAS __attribute__((address_space(3)))
; __device__ __forceinline__ unsigned cvt_pk_bf16(float lo, float hi) { unsigned r; asm volatile("v_cvt_pk_bf16_f32 %0, %1, %2" : "=v"(r) : "v"(lo), "v"(hi)); return r; }
; __device__ void phase0(const Params& P, LAS unsigned char* lds, const int G, const int bid) {
;     ...
;               for (int i = 0; i < 4; ++i) { v[i] = v[i] * rstd * w4[i];
;                   u32x2 w; w.x = cvt_pk_bf16(v[i][0], v[i][1]); w.y = cvt_pk_bf16(v[i][2], v[i][3]);
;                   *(u32x2*)(abf + (size_t)row * DM + 4 * lane + 256 * i) = w;
; #pragma unroll
;                   for (int j = 0; j < 4; ++j) { const LAS float* wr_ = wg + (j * 256 + i * 64 + lane) * 20; const float a = v[i][j];
; #pragma unroll
;                       for (int q = 0; q < 4; ++q) { const f32x4 wv = *(const LAS f32x4*)(wr_ + 4 * q);
;                           ga[4 * q] += a * wv[0]; ga[4 * q + 1] += a * wv[1]; ga[4 * q + 2] += a * wv[2]; ga[4 * q + 3] += a * wv[3]; } } }
	v_fma_f32 v87, v141, v138, 0
	v_fma_f32 v85, v142, v138, 0
	v_fma_f32 v83, v143, v138, 0
	s_waitcnt lgkmcnt(10)
	v_fma_f32 v120, v144, v138, 0
	v_fma_f32 v119, v145, v138, 0
	v_fma_f32 v118, v146, v138, 0
	v_fma_f32 v117, v147, v138, 0
	s_waitcnt lgkmcnt(9)
	v_fmac_f32_e32 v85, v150, v139
	v_fmac_f32_e32 v83, v151, v139
	s_waitcnt lgkmcnt(8)
	v_fmac_f32_e32 v120, v152, v139
	v_fmac_f32_e32 v119, v153, v139
	v_fmac_f32_e32 v118, v154, v139
	v_fmac_f32_e32 v117, v155, v139
	ds_read_b128 v[222:225], v103 offset:61440
	ds_read_b128 v[226:229], v103 offset:61456
	v_fmac_f32_e32 v87, v149, v139
	v_fma_f32 v116, v140, v138, 0
	v_fmac_f32_e32 v116, v148, v139
	s_waitcnt lgkmcnt(9)
	v_fma_f32 v125, v156, v138, 0
	v_fma_f32 v123, v157, v138, 0
	v_fma_f32 v122, v158, v138, 0
	v_fma_f32 v121, v159, v138, 0
	ds_read_b128 v[230:233], v103 offset:61472
	ds_read_b128 v[234:237], v103 offset:61488
	s_waitcnt lgkmcnt(10)
	v_fma_f32 v124, v173, v138, 0
	v_pk_mul_f32 v[76:77], v[8:9], v[76:77]
	v_pk_mul_f32 v[72:73], v[72:73], v[90:91] op_sel_hi:[1,0]
	s_waitcnt lgkmcnt(9)
	v_fmac_f32_e32 v125, v174, v139
	v_fmac_f32_e32 v123, v175, v139
	v_fmac_f32_e32 v122, v176, v139
	v_fma_f32 v128, v170, v138, 0
	v_fma_f32 v127, v171, v138, 0
	v_fma_f32 v126, v172, v138, 0
	s_waitcnt lgkmcnt(8)
	v_fmac_f32_e32 v128, v178, v139
	v_fmac_f32_e32 v127, v179, v139
	v_fmac_f32_e32 v126, v180, v139
	v_fmac_f32_e32 v124, v181, v139
	ds_read_b128 v[144:147], v102 offset:46080
	ds_read_b128 v[152:155], v102 offset:46096
	v_fmac_f32_e32 v121, v177, v139
	v_pk_mul_f32 v[72:73], v[12:13], v[72:73]
	v_pk_mul_f32 v[66:67], v[66:67], v[90:91] op_sel_hi:[1,0]
	s_waitcnt lgkmcnt(9)
	v_fmac_f32_e32 v116, v182, v92
	v_fmac_f32_e32 v87, v183, v92
	v_fmac_f32_e32 v85, v184, v92
	v_fmac_f32_e32 v83, v185, v92
	s_waitcnt lgkmcnt(8)
	v_fmac_f32_e32 v120, v188, v92
	v_fmac_f32_e32 v119, v189, v92
	v_fmac_f32_e32 v118, v190, v92
	v_fmac_f32_e32 v117, v191, v92
	ds_read_b128 v[140:143], v102 offset:46112
	ds_read_b128 v[148:151], v102 offset:46128
	v_pk_mul_f32 v[68:69], v[68:69], v[90:91] op_sel_hi:[1,0]
	s_waitcnt lgkmcnt(9)
	v_fmac_f32_e32 v125, v192, v92
	v_fmac_f32_e32 v123, v193, v92
	v_fmac_f32_e32 v122, v194, v92
	v_fmac_f32_e32 v121, v195, v92
	s_waitcnt lgkmcnt(8)
	v_fmac_f32_e32 v128, v196, v92
	v_fmac_f32_e32 v127, v197, v92
	v_fmac_f32_e32 v126, v198, v92
	v_fmac_f32_e32 v124, v199, v92
	ds_read_b128 v[156:159], v103 offset:25600
	ds_read_b128 v[170:173], v103 offset:25616
	v_pk_mul_f32 v[68:69], v[16:17], v[68:69]
	s_waitcnt lgkmcnt(9)
	v_fmac_f32_e32 v116, v222, v93
	v_fmac_f32_e32 v87, v223, v93
	v_fmac_f32_e32 v85, v224, v93
	v_fmac_f32_e32 v83, v225, v93
	s_waitcnt lgkmcnt(8)
	v_fmac_f32_e32 v120, v226, v93
	v_fmac_f32_e32 v119, v227, v93
	v_fmac_f32_e32 v118, v228, v93
	v_fmac_f32_e32 v117, v229, v93
	ds_read_b128 v[178:181], v103 offset:25632
	ds_read_b128 v[174:177], v103 offset:25648
	s_waitcnt lgkmcnt(9)
	v_fmac_f32_e32 v125, v230, v93
	v_fmac_f32_e32 v123, v231, v93
	v_fmac_f32_e32 v122, v232, v93
	v_fmac_f32_e32 v121, v233, v93
	s_waitcnt lgkmcnt(8)
	v_fmac_f32_e32 v128, v234, v93
	v_fmac_f32_e32 v127, v235, v93
	v_fmac_f32_e32 v126, v236, v93
	v_fmac_f32_e32 v124, v237, v93
	v_lshlrev_b64 v[92:93], 11, v[88:89]
	v_lshl_add_u64 v[92:93], v[80:81], 0, v[92:93]
	global_store_dwordx2 v[92:93], v[94:95], off
	v_pk_mul_f32 v[94:95], v[6:7], v[74:75]
	s_nop 0
	v_cvt_pk_bf16_f32 v74, v94, v95
	v_cvt_pk_bf16_f32 v75, v76, v77
	ds_read_b128 v[182:185], v103 offset:46080
	ds_read_b128 v[188:191], v103 offset:46096
	s_waitcnt lgkmcnt(9)
	v_fmac_f32_e32 v116, v144, v94
	v_fmac_f32_e32 v87, v145, v94
	v_fmac_f32_e32 v85, v146, v94
	v_fmac_f32_e32 v83, v147, v94
	s_waitcnt lgkmcnt(8)
	v_fmac_f32_e32 v120, v152, v94
	v_fmac_f32_e32 v119, v153, v94
	v_fmac_f32_e32 v118, v154, v94
	v_fmac_f32_e32 v117, v155, v94
	ds_read_b128 v[192:195], v103 offset:46112
	ds_read_b128 v[196:199], v103 offset:46128
	s_waitcnt lgkmcnt(9)
	v_fmac_f32_e32 v125, v140, v94
	v_fmac_f32_e32 v123, v141, v94
	v_fmac_f32_e32 v122, v142, v94
	v_fmac_f32_e32 v121, v143, v94
	s_waitcnt lgkmcnt(8)
	v_fmac_f32_e32 v128, v148, v94
	v_fmac_f32_e32 v127, v149, v94
	v_fmac_f32_e32 v126, v150, v94
	v_fmac_f32_e32 v124, v151, v94
	ds_read_b128 v[222:225], v104
	ds_read_b128 v[226:229], v105
	s_waitcnt lgkmcnt(9)
	v_fmac_f32_e32 v116, v156, v95
	v_fmac_f32_e32 v87, v157, v95
	v_fmac_f32_e32 v85, v158, v95
	v_fmac_f32_e32 v83, v159, v95
	s_waitcnt lgkmcnt(8)
	v_fmac_f32_e32 v120, v170, v95
	v_fmac_f32_e32 v119, v171, v95
	v_fmac_f32_e32 v118, v172, v95
	v_fmac_f32_e32 v117, v173, v95
	ds_read_b128 v[230:233], v106
	ds_read_b128 v[234:237], v107
	s_waitcnt lgkmcnt(9)
	v_fmac_f32_e32 v125, v95, v178
	v_fmac_f32_e32 v123, v95, v179
	v_fmac_f32_e32 v122, v95, v180
	v_fmac_f32_e32 v121, v95, v181
	s_waitcnt lgkmcnt(8)
	v_fmac_f32_e32 v128, v95, v174
	v_fmac_f32_e32 v127, v95, v175
	v_fmac_f32_e32 v126, v95, v176
	v_fmac_f32_e32 v124, v95, v177
	ds_read_b128 v[144:147], v102 offset:51200
	ds_read_b128 v[152:155], v102 offset:51216
	v_pk_mul_f32 v[94:95], v[10:11], v[70:71]
	s_waitcnt lgkmcnt(9)
	v_fmac_f32_e32 v116, v76, v182
	v_fmac_f32_e32 v87, v76, v183
	v_fmac_f32_e32 v85, v76, v184
	v_fmac_f32_e32 v83, v76, v185
	s_waitcnt lgkmcnt(8)
	v_fmac_f32_e32 v120, v76, v188
	v_fmac_f32_e32 v119, v76, v189
	v_fmac_f32_e32 v118, v76, v190
	v_fmac_f32_e32 v117, v76, v191
	ds_read_b128 v[140:143], v102 offset:51232
	ds_read_b128 v[148:151], v102 offset:51248
	s_waitcnt lgkmcnt(9)
	v_fmac_f32_e32 v125, v76, v192
	v_fmac_f32_e32 v123, v76, v193
	v_fmac_f32_e32 v122, v76, v194
	v_fmac_f32_e32 v121, v76, v195
	s_waitcnt lgkmcnt(8)
; #define LAS __attribute__((address_space(3)))
; __device__ __forceinline__ unsigned cvt_pk_bf16(float lo, float hi) { unsigned r; asm volatile("v_cvt_pk_bf16_f32 %0, %1, %2" : "=v"(r) : "v"(lo), "v"(hi)); return r; }
; __device__ void phase0(const Params& P, LAS unsigned char* lds, const int G, const int bid) {
;     ...
;               for (int i = 0; i < 4; ++i) { v[i] = v[i] * rstd * w4[i];
;                   u32x2 w; w.x = cvt_pk_bf16(v[i][0], v[i][1]); w.y = cvt_pk_bf16(v[i][2], v[i][3]);
;                   *(u32x2*)(abf + (size_t)row * DM + 4 * lane + 256 * i) = w;
; #pragma unroll
;                   for (int j = 0; j < 4; ++j) { const LAS float* wr_ = wg + (j * 256 + i * 64 + lane) * 20; const float a = v[i][j];
; #pragma unroll
;                       for (int q = 0; q < 4; ++q) { const f32x4 wv = *(const LAS f32x4*)(wr_ + 4 * q);
;                           ga[4 * q] += a * wv[0]; ga[4 * q + 1] += a * wv[1]; ga[4 * q + 2] += a * wv[2]; ga[4 * q + 3] += a * wv[3]; } } }
	v_fmac_f32_e32 v128, v76, v196
	v_fmac_f32_e32 v127, v76, v197
	v_fmac_f32_e32 v126, v76, v198
	v_fmac_f32_e32 v124, v76, v199
	ds_read_b128 v[156:159], v103 offset:30720
	ds_read_b128 v[170:173], v103 offset:30736
	s_waitcnt lgkmcnt(9)
	v_fmac_f32_e32 v116, v77, v222
	v_fmac_f32_e32 v87, v77, v223
	v_fmac_f32_e32 v85, v77, v224
	v_fmac_f32_e32 v83, v77, v225
	s_waitcnt lgkmcnt(8)
	v_fmac_f32_e32 v120, v77, v226
	v_fmac_f32_e32 v119, v77, v227
	v_fmac_f32_e32 v118, v77, v228
	v_fmac_f32_e32 v117, v77, v229
	ds_read_b128 v[178:181], v103 offset:30752
	ds_read_b128 v[174:177], v103 offset:30768
	global_store_dwordx2 v[92:93], v[74:75], off offset:512
	v_cvt_pk_bf16_f32 v70, v94, v95
	v_cvt_pk_bf16_f32 v71, v72, v73
	s_waitcnt lgkmcnt(9)
	v_fmac_f32_e32 v125, v77, v230
	v_fmac_f32_e32 v123, v77, v231
	v_fmac_f32_e32 v122, v77, v232
	v_fmac_f32_e32 v121, v77, v233
	s_waitcnt lgkmcnt(8)
	v_fmac_f32_e32 v128, v77, v234
	v_fmac_f32_e32 v127, v77, v235
	v_fmac_f32_e32 v126, v77, v236
	v_fmac_f32_e32 v124, v77, v237
	ds_read_b128 v[182:185], v103 offset:51200
	ds_read_b128 v[188:191], v103 offset:51216
	s_waitcnt lgkmcnt(9)
	v_fmac_f32_e32 v116, v94, v144
	v_fmac_f32_e32 v87, v94, v145
	v_fmac_f32_e32 v85, v94, v146
	v_fmac_f32_e32 v83, v94, v147
	s_waitcnt lgkmcnt(8)
	v_fmac_f32_e32 v120, v94, v152
	v_fmac_f32_e32 v119, v94, v153
	v_fmac_f32_e32 v118, v94, v154
	v_fmac_f32_e32 v117, v94, v155
	ds_read_b128 v[192:195], v103 offset:51232
	ds_read_b128 v[196:199], v103 offset:51248
	s_waitcnt lgkmcnt(9)
	v_fmac_f32_e32 v125, v94, v140
	v_fmac_f32_e32 v123, v94, v141
	v_fmac_f32_e32 v122, v94, v142
	v_fmac_f32_e32 v121, v94, v143
	s_waitcnt lgkmcnt(8)
	v_fmac_f32_e32 v128, v94, v148
	v_fmac_f32_e32 v127, v94, v149
	v_fmac_f32_e32 v126, v94, v150
	v_fmac_f32_e32 v124, v94, v151
	ds_read_b128 v[222:225], v108
	ds_read_b128 v[226:229], v109
	s_waitcnt lgkmcnt(9)
	v_fmac_f32_e32 v116, v95, v156
	v_fmac_f32_e32 v87, v95, v157
	v_fmac_f32_e32 v85, v95, v158
	v_fmac_f32_e32 v83, v95, v159
	s_waitcnt lgkmcnt(8)
	v_fmac_f32_e32 v120, v95, v170
	v_fmac_f32_e32 v119, v95, v171
	v_fmac_f32_e32 v118, v95, v172
	v_fmac_f32_e32 v117, v95, v173
	ds_read_b128 v[230:233], v110
	ds_read_b128 v[234:237], v111
	s_waitcnt lgkmcnt(9)
	v_fmac_f32_e32 v125, v95, v178
	v_fmac_f32_e32 v123, v95, v179
	v_fmac_f32_e32 v122, v95, v180
	v_fmac_f32_e32 v121, v95, v181
	s_waitcnt lgkmcnt(8)
	v_fmac_f32_e32 v128, v95, v174
	v_fmac_f32_e32 v127, v95, v175
	v_fmac_f32_e32 v126, v95, v176
	v_fmac_f32_e32 v124, v95, v177
	ds_read_b128 v[144:147], v102 offset:56320
	ds_read_b128 v[152:155], v102 offset:56336
	v_pk_mul_f32 v[94:95], v[14:15], v[66:67]
	s_waitcnt lgkmcnt(9)
	v_fmac_f32_e32 v116, v72, v182
	v_fmac_f32_e32 v87, v72, v183
	v_fmac_f32_e32 v85, v72, v184
	v_fmac_f32_e32 v83, v72, v185
	s_waitcnt lgkmcnt(8)
	v_fmac_f32_e32 v120, v72, v188
	v_fmac_f32_e32 v119, v72, v189
	v_fmac_f32_e32 v118, v72, v190
	v_fmac_f32_e32 v117, v72, v191
	ds_read_b128 v[140:143], v102 offset:56352
	ds_read_b128 v[148:151], v102 offset:56368
	s_waitcnt lgkmcnt(9)
	v_fmac_f32_e32 v125, v72, v192
	v_fmac_f32_e32 v123, v72, v193
	v_fmac_f32_e32 v122, v72, v194
	v_fmac_f32_e32 v121, v72, v195
	s_waitcnt lgkmcnt(8)
	v_fmac_f32_e32 v128, v72, v196
	v_fmac_f32_e32 v127, v72, v197
	v_fmac_f32_e32 v126, v72, v198
	v_fmac_f32_e32 v124, v72, v199
	ds_read_b128 v[156:159], v103 offset:35840
	ds_read_b128 v[170:173], v103 offset:35856
	s_waitcnt lgkmcnt(9)
	v_fmac_f32_e32 v116, v73, v222
	v_fmac_f32_e32 v87, v73, v223
	v_fmac_f32_e32 v85, v73, v224
	v_fmac_f32_e32 v83, v73, v225
	s_waitcnt lgkmcnt(8)
	v_fmac_f32_e32 v120, v73, v226
	v_fmac_f32_e32 v119, v73, v227
	v_fmac_f32_e32 v118, v73, v228
	v_fmac_f32_e32 v117, v73, v229
	ds_read_b128 v[178:181], v103 offset:35872
	ds_read_b128 v[174:177], v103 offset:35888
	global_store_dwordx2 v[92:93], v[70:71], off offset:1024
	v_cvt_pk_bf16_f32 v66, v94, v95
	v_cvt_pk_bf16_f32 v67, v68, v69
	s_waitcnt lgkmcnt(9)
	v_fmac_f32_e32 v125, v73, v230
	v_fmac_f32_e32 v123, v73, v231
	v_fmac_f32_e32 v122, v73, v232
	v_fmac_f32_e32 v121, v73, v233
	s_waitcnt lgkmcnt(8)
	v_fmac_f32_e32 v128, v73, v234
	v_fmac_f32_e32 v127, v73, v235
	v_fmac_f32_e32 v126, v73, v236
	v_fmac_f32_e32 v124, v73, v237
	ds_read_b128 v[182:185], v103 offset:56320
	ds_read_b128 v[188:191], v103 offset:56336
	s_waitcnt lgkmcnt(9)
	v_fmac_f32_e32 v116, v94, v144
	v_fmac_f32_e32 v87, v94, v145
	v_fmac_f32_e32 v85, v94, v146
	v_fmac_f32_e32 v83, v94, v147
	s_waitcnt lgkmcnt(8)
	v_fmac_f32_e32 v120, v94, v152
	v_fmac_f32_e32 v119, v94, v153
	v_fmac_f32_e32 v118, v94, v154
	v_fmac_f32_e32 v117, v94, v155
	ds_read_b128 v[192:195], v103 offset:56352
	ds_read_b128 v[196:199], v103 offset:56368
	s_waitcnt lgkmcnt(9)
	v_fmac_f32_e32 v125, v94, v140
	v_fmac_f32_e32 v123, v94, v141
	v_fmac_f32_e32 v122, v94, v142
	v_fmac_f32_e32 v121, v94, v143
	s_waitcnt lgkmcnt(8)
	v_fmac_f32_e32 v128, v94, v148
	v_fmac_f32_e32 v127, v94, v149
	v_fmac_f32_e32 v126, v94, v150
	v_fmac_f32_e32 v124, v94, v151
	ds_read_b128 v[222:225], v112
	ds_read_b128 v[226:229], v113
	s_waitcnt lgkmcnt(9)
	v_fmac_f32_e32 v116, v95, v156
	v_fmac_f32_e32 v87, v95, v157
	v_fmac_f32_e32 v85, v95, v158
	v_fmac_f32_e32 v83, v95, v159
	s_waitcnt lgkmcnt(8)
	v_fmac_f32_e32 v120, v95, v170
	v_fmac_f32_e32 v119, v95, v171
	v_fmac_f32_e32 v118, v95, v172
	v_fmac_f32_e32 v117, v95, v173
	ds_read_b128 v[230:233], v114
	ds_read_b128 v[234:237], v115
	s_waitcnt lgkmcnt(9)
	v_fmac_f32_e32 v125, v95, v178
	v_fmac_f32_e32 v123, v95, v179
	v_fmac_f32_e32 v122, v95, v180
	v_fmac_f32_e32 v121, v95, v181
	s_waitcnt lgkmcnt(8)
; #define LAS __attribute__((address_space(3)))
; __device__ __forceinline__ unsigned cvt_pk_bf16(float lo, float hi) { unsigned r; asm volatile("v_cvt_pk_bf16_f32 %0, %1, %2" : "=v"(r) : "v"(lo), "v"(hi)); return r; }
; __device__ void phase0(const Params& P, LAS unsigned char* lds, const int G, const int bid) {
;     ...
;               for (int i = 0; i < 4; ++i) { v[i] = v[i] * rstd * w4[i];
;                   u32x2 w; w.x = cvt_pk_bf16(v[i][0], v[i][1]); w.y = cvt_pk_bf16(v[i][2], v[i][3]);
;                   *(u32x2*)(abf + (size_t)row * DM + 4 * lane + 256 * i) = w;
; #pragma unroll
;                   for (int j = 0; j < 4; ++j) { const LAS float* wr_ = wg + (j * 256 + i * 64 + lane) * 20; const float a = v[i][j];
; #pragma unroll
;                       for (int q = 0; q < 4; ++q) { const f32x4 wv = *(const LAS f32x4*)(wr_ + 4 * q);
;                           ga[4 * q] += a * wv[0]; ga[4 * q + 1] += a * wv[1]; ga[4 * q + 2] += a * wv[2]; ga[4 * q + 3] += a * wv[3]; } } }
;               float r8[8], r4[4], r2[2], r1;
; #pragma unroll
;               for (int c = 0; c < 8; ++c) { const bool hi = (lane & 32) != 0; const float send = hi ? ga[c] : ga[c + 8], keep = hi ? ga[c + 8] : ga[c]; r8[c] = keep + __shfl_xor(send, 32); }
; #pragma unroll
;               for (int c = 0; c < 4; ++c) { const bool hi = (lane & 16) != 0; const float send = hi ? r8[c] : r8[c + 4], keep = hi ? r8[c + 4] : r8[c]; r4[c] = keep + __shfl_xor(send, 16); }
; #pragma unroll
;               for (int c = 0; c < 2; ++c) { const bool hi = (lane & 8) != 0; const float send = hi ? r4[c] : r4[c + 2], keep = hi ? r4[c + 2] : r4[c]; r2[c] = keep + __shfl_xor(send, 8); }
;               { const bool hi = (lane & 4) != 0; const float send = hi ? r2[0] : r2[1], keep = hi ? r2[1] : r2[0]; r1 = keep + __shfl_xor(send, 4); }
;               r1 += __shfl_xor(r1, 2); r1 += __shfl_xor(r1, 1);
	v_fmac_f32_e32 v128, v95, v174
	v_fmac_f32_e32 v127, v95, v175
	v_fmac_f32_e32 v126, v95, v176
	v_fmac_f32_e32 v124, v95, v177
	s_waitcnt lgkmcnt(7)
	v_fmac_f32_e32 v116, v68, v182
	v_fmac_f32_e32 v87, v68, v183
	v_fmac_f32_e32 v85, v68, v184
	v_fmac_f32_e32 v83, v68, v185
	s_waitcnt lgkmcnt(6)
	v_fmac_f32_e32 v120, v68, v188
	v_fmac_f32_e32 v119, v68, v189
	v_fmac_f32_e32 v118, v68, v190
	v_fmac_f32_e32 v117, v68, v191
	s_waitcnt lgkmcnt(5)
	v_fmac_f32_e32 v125, v68, v192
	v_fmac_f32_e32 v123, v68, v193
	v_fmac_f32_e32 v122, v68, v194
	v_fmac_f32_e32 v121, v68, v195
	s_waitcnt lgkmcnt(4)
	v_fmac_f32_e32 v128, v68, v196
	v_fmac_f32_e32 v127, v68, v197
	v_fmac_f32_e32 v126, v68, v198
	v_fmac_f32_e32 v124, v68, v199
	s_waitcnt lgkmcnt(3)
	v_fmac_f32_e32 v116, v69, v222
	v_fmac_f32_e32 v87, v69, v223
	v_fmac_f32_e32 v85, v69, v224
	v_fmac_f32_e32 v83, v69, v225
	s_waitcnt lgkmcnt(2)
	v_fmac_f32_e32 v120, v69, v226
	v_fmac_f32_e32 v119, v69, v227
	v_fmac_f32_e32 v118, v69, v228
	v_fmac_f32_e32 v117, v69, v229
	global_store_dwordx2 v[92:93], v[66:67], off offset:1536
	s_waitcnt lgkmcnt(1)
	v_fmac_f32_e32 v125, v69, v230
	v_fmac_f32_e32 v123, v69, v231
	v_cndmask_b32_e32 v68, v116, v125, vcc
	v_fmac_f32_e32 v122, v69, v232
	ds_bpermute_b32 v68, v96, v68
	v_cndmask_b32_e32 v70, v87, v123, vcc
	ds_bpermute_b32 v70, v96, v70
	v_cndmask_b32_e32 v71, v85, v122, vcc
	ds_bpermute_b32 v71, v96, v71
	v_fmac_f32_e32 v121, v69, v233
	s_waitcnt lgkmcnt(3)
	v_fmac_f32_e32 v128, v69, v234
	v_fmac_f32_e32 v127, v69, v235
	v_fmac_f32_e32 v126, v69, v236
	v_fmac_f32_e32 v124, v69, v237
	v_cndmask_b32_e32 v69, v125, v116, vcc
	s_waitcnt lgkmcnt(2)
	v_add_f32_e32 v68, v69, v68
	v_cndmask_b32_e32 v69, v123, v87, vcc
	s_waitcnt lgkmcnt(1)
	v_add_f32_e32 v69, v69, v70
	v_cndmask_b32_e32 v70, v122, v85, vcc
	s_waitcnt lgkmcnt(0)
	v_add_f32_e32 v70, v70, v71
	v_cndmask_b32_e32 v71, v83, v121, vcc
	ds_bpermute_b32 v71, v96, v71
	v_cndmask_b32_e32 v73, v120, v128, vcc
	ds_bpermute_b32 v73, v96, v73
	v_cndmask_b32_e32 v74, v119, v127, vcc
	ds_bpermute_b32 v74, v96, v74
	v_cndmask_b32_e32 v72, v121, v83, vcc
	s_waitcnt lgkmcnt(2)
	v_add_f32_e32 v71, v72, v71
	v_cndmask_b32_e32 v72, v128, v120, vcc
	s_waitcnt lgkmcnt(1)
	v_add_f32_e32 v72, v72, v73
	v_cndmask_b32_e32 v73, v127, v119, vcc
	s_waitcnt lgkmcnt(0)
	v_add_f32_e32 v73, v73, v74
	v_cndmask_b32_e32 v74, v118, v126, vcc
	ds_bpermute_b32 v74, v96, v74
	v_cndmask_b32_e32 v76, v117, v124, vcc
	ds_bpermute_b32 v76, v96, v76
	v_cndmask_b32_e32 v75, v126, v118, vcc
	v_cndmask_b32_e64 v77, v68, v72, s[42:43]
	s_waitcnt lgkmcnt(1)
	v_add_f32_e32 v74, v75, v74
	v_cndmask_b32_e32 v75, v124, v117, vcc
	s_waitcnt lgkmcnt(0)
	v_add_f32_e32 v75, v75, v76
	v_cndmask_b32_e64 v68, v72, v68, s[42:43]
	v_cndmask_b32_e64 v72, v69, v73, s[42:43]
	v_cndmask_b32_e64 v69, v73, v69, s[42:43]
	v_cndmask_b32_e64 v73, v70, v74, s[42:43]
	v_cndmask_b32_e64 v76, v71, v75, s[42:43]
	ds_bpermute_b32 v77, v97, v77
	ds_bpermute_b32 v72, v97, v72
	ds_bpermute_b32 v73, v97, v73
	ds_bpermute_b32 v76, v97, v76
	v_cndmask_b32_e64 v70, v74, v70, s[42:43]
	v_cndmask_b32_e64 v71, v75, v71, s[42:43]
	s_waitcnt lgkmcnt(3)
	v_add_f32_e32 v68, v68, v77
	s_waitcnt lgkmcnt(2)
	v_add_f32_e32 v69, v69, v72
	s_waitcnt lgkmcnt(1)
	v_add_f32_e32 v70, v70, v73
	s_waitcnt lgkmcnt(0)
	v_add_f32_e32 v71, v71, v76
	v_cndmask_b32_e64 v72, v68, v70, s[44:45]
	v_cndmask_b32_e64 v73, v69, v71, s[44:45]
	ds_bpermute_b32 v72, v98, v72
	ds_bpermute_b32 v73, v98, v73
	v_cndmask_b32_e64 v68, v70, v68, s[44:45]
	v_cndmask_b32_e64 v69, v71, v69, s[44:45]
	s_waitcnt lgkmcnt(1)
	v_add_f32_e32 v68, v68, v72
	s_waitcnt lgkmcnt(0)
	v_add_f32_e32 v69, v69, v73
	v_cndmask_b32_e64 v70, v68, v69, s[46:47]
	ds_bpermute_b32 v70, v99, v70
	v_cndmask_b32_e64 v68, v69, v68, s[46:47]
	s_waitcnt lgkmcnt(0)
	v_add_f32_e32 v68, v68, v70
	ds_bpermute_b32 v69, v100, v68
	s_waitcnt lgkmcnt(0)
	v_add_f32_e32 v68, v68, v69
	ds_bpermute_b32 v69, v101, v68
	s_and_saveexec_b64 s[6:7], s[48:49]
	s_cbranch_execz .LBB0_1050
	s_waitcnt lgkmcnt(0)
	v_add_f32_e32 v66, v68, v69
	v_add_f32_e32 v66, v91, v66
	s_and_saveexec_b64 s[8:9], s[40:41]
	s_cbranch_execz .LBB0_1049
; __device__ __forceinline__ float logsigmoidf_(float x) { return fminf(x, 0.0f) - log1pf(__expf(-fabsf(x))); }
; __device__ void phase0(const Params& P, LAS unsigned char* lds, const int G, const int bid) {
;     ...
;               { const bool hi = (lane & 4) != 0; const float send = hi ? r2[0] : r2[1], keep = hi ? r2[1] : r2[0]; r1 = keep + __shfl_xor(send, 4); }
;               r1 += __shfl_xor(r1, 2); r1 += __shfl_xor(r1, 1);
;               if ((lane & 3) == 0) { float gv = r1 + gbias; if (gcol >= 8) gv = logsigmoidf_(gv); gates[(size_t)row * 16 + gcol] = gv; }
	s_mov_b32 s12, 0xbfb8aa3b
	v_mul_f32_e64 v67, |v66|, s12
	v_exp_f32_e32 v83, v67
	v_max_f32_e32 v66, v66, v66
	v_min_f32_e32 v85, 0, v66
	s_mov_b32 s12, 0x3f2aaaab
	v_add_f32_e32 v68, 1.0, v83
	v_add_f32_e32 v66, -1.0, v68
	v_sub_f32_e32 v67, v66, v68
	v_sub_f32_e32 v66, v83, v66
	v_add_f32_e32 v67, 1.0, v67
	v_add_f32_e32 v69, v66, v67
	v_frexp_mant_f32_e32 v70, v68
	v_cvt_f64_f32_e32 v[66:67], v68
	v_frexp_exp_i32_f64_e32 v66, v[66:67]
	v_cmp_gt_f32_e64 s[50:51], s12, v70
	s_mov_b32 s12, 0x3f317218
	s_nop 0
	v_subbrev_co_u32_e64 v74, s[50:51], 0, v66, s[50:51]
	v_sub_u32_e32 v66, 0, v74
	v_ldexp_f32 v67, v68, v66
	v_add_f32_e32 v68, -1.0, v67
	v_add_f32_e32 v70, 1.0, v67
	v_ldexp_f32 v66, v69, v66
	v_add_f32_e32 v69, 1.0, v68
	v_add_f32_e32 v71, -1.0, v70
	v_sub_f32_e32 v69, v67, v69
	v_sub_f32_e32 v67, v67, v71
	v_add_f32_e32 v69, v66, v69
	v_add_f32_e32 v66, v66, v67
	v_add_f32_e32 v75, v70, v66
	v_rcp_f32_e32 v77, v75
	v_sub_f32_e32 v67, v75, v70
	v_sub_f32_e32 v76, v66, v67
	v_add_f32_e32 v67, v68, v69
	v_mul_f32_e32 v90, v67, v77
	v_sub_f32_e32 v66, v67, v68
	v_mul_f32_e32 v68, v75, v90
	v_fma_f32 v70, v90, v75, -v68
	v_fmac_f32_e32 v70, v90, v76
	v_sub_f32_e32 v87, v69, v66
	v_add_f32_e32 v66, v68, v70
	v_sub_f32_e32 v69, v67, v66
	v_pk_add_f32 v[72:73], v[66:67], v[68:69] neg_lo:[0,1] neg_hi:[0,1]
	v_mov_b32_e32 v71, v66
	v_pk_add_f32 v[66:67], v[72:73], v[70:71] neg_lo:[0,1] neg_hi:[0,1]
	s_nop 0
	v_add_f32_e32 v67, v87, v67
	v_add_f32_e32 v66, v66, v67
	v_add_f32_e32 v67, v69, v66
	v_mul_f32_e32 v87, v77, v67
	v_mul_f32_e32 v68, v75, v87
	v_fma_f32 v70, v87, v75, -v68
	v_fmac_f32_e32 v70, v87, v76
	v_sub_f32_e32 v69, v69, v67
	v_add_f32_e32 v75, v66, v69
	v_add_f32_e32 v66, v68, v70
	v_sub_f32_e32 v69, v67, v66
	v_pk_add_f32 v[72:73], v[66:67], v[68:69] neg_lo:[0,1] neg_hi:[0,1]
	v_mov_b32_e32 v71, v66
	v_pk_add_f32 v[66:67], v[72:73], v[70:71] neg_lo:[0,1] neg_hi:[0,1]
	s_nop 0
	v_add_f32_e32 v67, v75, v67
	v_add_f32_e32 v66, v66, v67
	v_add_f32_e32 v67, v90, v87
	v_add_f32_e32 v66, v69, v66
	v_sub_f32_e32 v68, v67, v90
	v_mul_f32_e32 v66, v77, v66
	v_sub_f32_e32 v68, v87, v68
	v_add_f32_e32 v68, v68, v66
	v_add_f32_e32 v70, v67, v68
	v_mul_f32_e32 v71, v70, v70
	v_fmamk_f32 v66, v71, 0x3e9b6dac, v208
	v_fmaak_f32 v169, v71, v66, 0x3f2aaada
	v_cvt_f32_i32_e32 v66, v74
	v_sub_f32_e32 v67, v70, v67
	v_sub_f32_e32 v67, v68, v67
	v_ldexp_f32 v72, v67, 1
	v_mul_f32_e32 v67, v70, v71
	v_ldexp_f32 v69, v70, 1
	v_pk_mul_f32 v[70:71], v[66:67], v[168:169]
	s_nop 0
	v_fma_f32 v68, v66, s12, -v70
	v_fmac_f32_e32 v68, 0xb102e308, v66
	v_pk_add_f32 v[66:67], v[70:71], v[68:69]
	s_mov_b32 s12, 0x7f800000
	v_sub_f32_e32 v69, v67, v69
	v_sub_f32_e32 v69, v71, v69
	v_add_f32_e32 v73, v72, v69
	v_mov_b32_e32 v72, v70
	v_pk_add_f32 v[70:71], v[66:67], v[70:71] neg_lo:[0,1] neg_hi:[0,1]
	v_pk_add_f32 v[74:75], v[66:67], v[72:73]
	v_mov_b32_e32 v69, v66
	v_mov_b32_e32 v71, v75
	v_pk_add_f32 v[76:77], v[68:69], v[70:71] neg_lo:[0,1] neg_hi:[0,1]
	v_pk_add_f32 v[68:69], v[68:69], v[70:71]
	v_mov_b32_e32 v72, v73
	v_pk_add_f32 v[70:71], v[68:69], v[66:67] op_sel:[1,0] op_sel_hi:[0,1] neg_lo:[0,1] neg_hi:[0,1]
	s_nop 0
	v_pk_add_f32 v[92:93], v[74:75], v[70:71] op_sel_hi:[1,0] neg_lo:[0,1] neg_hi:[0,1]
	v_mov_b32_e32 v74, v75
	v_mov_b32_e32 v75, v69
	v_pk_mov_b32 v[70:71], v[66:67], v[70:71] op_sel:[1,0]
	v_mov_b32_e32 v73, v66
	v_pk_add_f32 v[70:71], v[74:75], v[70:71] neg_lo:[0,1] neg_hi:[0,1]
	v_mov_b32_e32 v92, v76
	v_pk_add_f32 v[66:67], v[72:73], v[70:71] neg_lo:[0,1] neg_hi:[0,1]
	v_mov_b32_e32 v77, v69
	v_pk_add_f32 v[70:71], v[92:93], v[66:67]
	v_cmp_neq_f32_e64 s[50:51], s12, v83
	v_pk_add_f32 v[72:73], v[70:71], v[70:71] op_sel:[0,1] op_sel_hi:[1,0]
	s_mov_b32 s12, 0x33800000
	v_pk_add_f32 v[68:69], v[68:69], v[72:73] op_sel:[1,0] op_sel_hi:[0,1]
	s_nop 0
	v_mov_b32_e32 v71, v68
	v_pk_add_f32 v[74:75], v[70:71], v[76:77] neg_lo:[0,1] neg_hi:[0,1]
	v_mov_b32_e32 v67, v72
	v_sub_f32_e32 v69, v70, v74
	v_pk_add_f32 v[66:67], v[66:67], v[74:75] neg_lo:[0,1] neg_hi:[0,1]
	v_sub_f32_e32 v69, v76, v69
	v_add_f32_e32 v66, v66, v69
	v_add_f32_e32 v66, v66, v67
	v_add_f32_e32 v66, v68, v66
	v_cndmask_b32_e64 v66, v212, v66, s[50:51]
	v_cmp_ngt_f32_e64 s[50:51], -1.0, v83
	s_nop 1
	v_cndmask_b32_e64 v66, v213, v66, s[50:51]
	v_cmp_neq_f32_e64 s[50:51], -1.0, v83
	s_nop 1
	v_cndmask_b32_e64 v66, v214, v66, s[50:51]
	v_cmp_lt_f32_e64 s[50:51], |v83|, s12
	s_nop 1
	v_cndmask_b32_e64 v66, v66, v83, s[50:51]
	v_sub_f32_e32 v66, v85, v66

; #define LAS __attribute__((address_space(3)))
; __device__ __forceinline__ unsigned cvt_pk_bf16(float lo, float hi) { unsigned r; asm volatile("v_cvt_pk_bf16_f32 %0, %1, %2" : "=v"(r) : "v"(lo), "v"(hi)); return r; }
; __device__ void phase0(const Params& P, LAS unsigned char* lds, const int G, const int bid) {
;     ...
;           for (int rr = 0; rr < 4; ++rr) { const int row = row0 + rr * G * 8; if (row >= NTOK) continue;
;               f32x4 (&v)[4] = vv[rr]; float ss = 0.f;
; #pragma unroll
;               for (int i = 0; i < 4; ++i)
; #pragma unroll
;                   for (int j = 0; j < 4; ++j) ss += v[i][j] * v[i][j];
; #pragma unroll
;               for (int o = 32; o >= 1; o >>= 1) ss += __shfl_xor(ss, o);
;               const float rstd = rsqrtf(ss * (1.0f / DM) + 1e-6f);
;               float ga[16];
; #pragma unroll
;               for (int c = 0; c < 16; ++c) ga[c] = 0.f;
; #pragma unroll
;               for (int i = 0; i < 4; ++i) { v[i] = v[i] * rstd * w4[i];
;                   u32x2 w; w.x = cvt_pk_bf16(v[i][0], v[i][1]); w.y = cvt_pk_bf16(v[i][2], v[i][3]);
;                   *(u32x2*)(abf + (size_t)row * DM + 4 * lane + 256 * i) = w;
; #pragma unroll
;                   for (int j = 0; j < 4; ++j) { const LAS float* wr_ = wg + (j * 256 + i * 64 + lane) * 20; const float a = v[i][j];
; #pragma unroll
;                       for (int q = 0; q < 4; ++q) { const f32x4 wv = *(const LAS f32x4*)(wr_ + 4 * q);
;                           ga[4 * q] += a * wv[0]; ga[4 * q + 1] += a * wv[1]; ga[4 * q + 2] += a * wv[2]; ga[4 * q + 3] += a * wv[3]; } } }
.LBB0_1050:
	s_or_b64 exec, exec, s[6:7]
	v_cmp_gt_i32_e64 s[50:51], s15, v82
	s_and_saveexec_b64 s[6:7], s[50:51]
	s_cbranch_execz .LBB0_1055
	s_waitcnt vmcnt(15)
	v_mul_f32_e32 v70, v63, v63
	v_fmac_f32_e32 v70, v62, v62
	v_fmac_f32_e32 v70, v64, v64
	v_fmac_f32_e32 v70, v65, v65
	s_waitcnt vmcnt(14)
	v_fmac_f32_e32 v70, v58, v58
	v_fmac_f32_e32 v70, v59, v59
	v_fmac_f32_e32 v70, v60, v60
	v_fmac_f32_e32 v70, v61, v61
	s_waitcnt vmcnt(13)
	v_fmac_f32_e32 v70, v54, v54
	v_fmac_f32_e32 v70, v55, v55
	v_fmac_f32_e32 v70, v56, v56
	v_fmac_f32_e32 v70, v57, v57
	s_waitcnt vmcnt(12) lgkmcnt(0)
	v_pk_mul_f32 v[68:69], v[50:51], v[50:51]
	v_pk_mul_f32 v[66:67], v[52:53], v[52:53]
	v_add_f32_e32 v68, v68, v70
	v_add_f32_e32 v68, v69, v68
	v_add_f32_e32 v66, v66, v68
	v_add_f32_e32 v66, v67, v66
	ds_bpermute_b32 v67, v96, v66
	v_ashrrev_i32_e32 v83, 31, v82
	v_lshlrev_b64 v[68:69], 11, v[82:83]
	v_lshl_add_u64 v[68:69], v[80:81], 0, v[68:69]
	s_waitcnt lgkmcnt(0)
	v_add_f32_e32 v66, v66, v67
	ds_bpermute_b32 v67, v97, v66
	s_waitcnt lgkmcnt(0)
	v_add_f32_e32 v66, v66, v67
	ds_bpermute_b32 v67, v98, v66
	s_waitcnt lgkmcnt(0)
	v_add_f32_e32 v66, v66, v67
	ds_bpermute_b32 v67, v99, v66
	s_waitcnt lgkmcnt(0)
	v_add_f32_e32 v66, v66, v67
	ds_bpermute_b32 v67, v100, v66
	s_waitcnt lgkmcnt(0)
	v_add_f32_e32 v66, v66, v67
	ds_bpermute_b32 v67, v101, v66
	s_waitcnt lgkmcnt(0)
	v_add_f32_e32 v66, v66, v67
	v_fmamk_f32 v66, v66, 0x3a800000, v210
	v_cmp_gt_f32_e64 s[50:51], s30, v66
	v_mul_f32_e32 v67, 0x4b800000, v66
	s_nop 0
	v_cndmask_b32_e64 v66, v66, v67, s[50:51]
	v_rsq_f32_e32 v66, v66
	s_nop 0
	v_mul_f32_e32 v67, 0x45800000, v66
	v_cndmask_b32_e64 v66, v66, v67, s[50:51]
	v_pk_mul_f32 v[70:71], v[62:63], v[66:67] op_sel_hi:[1,0]
	v_pk_mul_f32 v[62:63], v[64:65], v[66:67] op_sel_hi:[1,0]
	v_pk_mul_f32 v[64:65], v[2:3], v[70:71]
	v_pk_mul_f32 v[62:63], v[4:5], v[62:63]
	v_cvt_pk_bf16_f32 v70, v64, v65
	s_nop 0
	v_cvt_pk_bf16_f32 v71, v62, v63
	global_store_dwordx2 v[68:69], v[70:71], off
	ds_read_b128 v[140:143], v102 offset:40960
	ds_read_b128 v[144:147], v102 offset:40976
	ds_read_b128 v[148:151], v102 offset:40992
	ds_read_b128 v[152:155], v102 offset:41008
	ds_read_b128 v[156:159], v102 offset:61440
	ds_read_b128 v[170:173], v102 offset:61456
	ds_read_b128 v[174:177], v102 offset:61472
	ds_read_b128 v[178:181], v102 offset:61488
	ds_read_b128 v[182:185], v103 offset:40960
	ds_read_b128 v[188:191], v103 offset:40976
	ds_read_b128 v[192:195], v103 offset:40992
	ds_read_b128 v[196:199], v103 offset:41008
	s_waitcnt lgkmcnt(11)
	v_fma_f32 v89, v140, v64, 0
	s_waitcnt lgkmcnt(10)
	v_fma_f32 v74, v144, v64, 0
	s_waitcnt lgkmcnt(9)
	v_fma_f32 v92, v148, v64, 0
	v_fma_f32 v90, v149, v64, 0
	v_fma_f32 v87, v150, v64, 0
	v_fma_f32 v77, v151, v64, 0
	ds_read_b128 v[222:225], v103 offset:61440
	v_fma_f32 v88, v141, v64, 0
	v_fma_f32 v85, v142, v64, 0
	v_fma_f32 v75, v143, v64, 0
	v_fma_f32 v72, v145, v64, 0
	s_waitcnt lgkmcnt(8)
	v_fmac_f32_e32 v89, v156, v65
	v_fmac_f32_e32 v88, v157, v65
	v_fmac_f32_e32 v85, v158, v65
	v_fmac_f32_e32 v75, v159, v65
	ds_read_b128 v[226:229], v103 offset:61456
	v_fma_f32 v70, v146, v64, 0
	v_fma_f32 v67, v147, v64, 0
	v_fma_f32 v76, v152, v64, 0
	v_fma_f32 v73, v153, v64, 0
	s_waitcnt lgkmcnt(8)
	v_fmac_f32_e32 v74, v170, v65
	v_fmac_f32_e32 v72, v171, v65
	v_fmac_f32_e32 v70, v172, v65
	v_fmac_f32_e32 v67, v173, v65
	ds_read_b128 v[230:233], v103 offset:61472
	v_fma_f32 v71, v154, v64, 0
	v_fma_f32 v64, v155, v64, 0
	s_waitcnt lgkmcnt(8)
	v_fmac_f32_e32 v92, v174, v65
	v_fmac_f32_e32 v90, v175, v65
	v_fmac_f32_e32 v87, v176, v65
	v_fmac_f32_e32 v77, v177, v65
	ds_read_b128 v[234:237], v103 offset:61488
	s_waitcnt lgkmcnt(8)
	v_fmac_f32_e32 v76, v178, v65
	v_fmac_f32_e32 v73, v179, v65
	v_fmac_f32_e32 v71, v180, v65
	v_fmac_f32_e32 v64, v181, v65
	ds_read_b128 v[148:151], v102 offset:46080
	ds_read_b128 v[140:143], v102 offset:46096
	ds_read_b128 v[156:159], v102 offset:46112
	ds_read_b128 v[144:147], v102 offset:46128
	s_waitcnt lgkmcnt(11)
	v_fmac_f32_e32 v89, v182, v62
	v_fmac_f32_e32 v88, v183, v62
	v_fmac_f32_e32 v85, v184, v62
	v_fmac_f32_e32 v75, v185, v62
	ds_read_b128 v[170:173], v103 offset:25600
	s_waitcnt lgkmcnt(11)
	v_fmac_f32_e32 v74, v62, v188
	v_fmac_f32_e32 v72, v62, v189
	v_fmac_f32_e32 v70, v62, v190
	v_fmac_f32_e32 v67, v62, v191
	s_waitcnt lgkmcnt(8)
	v_fmac_f32_e32 v89, v63, v222
	v_fmac_f32_e32 v88, v63, v223
	v_fmac_f32_e32 v85, v63, v224
	v_fmac_f32_e32 v75, v63, v225
	ds_read_b128 v[152:155], v103 offset:25616
	v_fmac_f32_e32 v92, v62, v192
	v_fmac_f32_e32 v90, v62, v193
	v_fmac_f32_e32 v87, v62, v194
	v_fmac_f32_e32 v77, v62, v195
	s_waitcnt lgkmcnt(8)
	v_fmac_f32_e32 v74, v63, v226
	v_fmac_f32_e32 v72, v63, v227
	v_fmac_f32_e32 v70, v63, v228
	v_fmac_f32_e32 v67, v63, v229
	ds_read_b128 v[174:177], v103 offset:25632
	v_fmac_f32_e32 v76, v62, v196
	v_fmac_f32_e32 v73, v62, v197
	v_fmac_f32_e32 v71, v62, v198
	v_fmac_f32_e32 v64, v62, v199
	s_waitcnt lgkmcnt(8)
	v_fmac_f32_e32 v92, v63, v230
	v_fmac_f32_e32 v90, v63, v231
	v_fmac_f32_e32 v87, v63, v232
	v_fmac_f32_e32 v77, v63, v233
	ds_read_b128 v[178:181], v103 offset:25648
	s_waitcnt lgkmcnt(8)
	v_fmac_f32_e32 v76, v63, v234
	v_fmac_f32_e32 v73, v63, v235
	v_fmac_f32_e32 v71, v63, v236
	v_fmac_f32_e32 v64, v63, v237
	v_pk_mul_f32 v[62:63], v[58:59], v[66:67] op_sel_hi:[1,0]
	v_pk_mul_f32 v[58:59], v[60:61], v[66:67] op_sel_hi:[1,0]
	v_pk_mul_f32 v[94:95], v[6:7], v[62:63]
	v_pk_mul_f32 v[58:59], v[8:9], v[58:59]
	v_cvt_pk_bf16_f32 v60, v94, v95
	s_nop 0
	v_cvt_pk_bf16_f32 v61, v58, v59
	global_store_dwordx2 v[68:69], v[60:61], off offset:512
	ds_read_b128 v[182:185], v103 offset:46080
	ds_read_b128 v[188:191], v103 offset:46096
	ds_read_b128 v[222:225], v103 offset:46112
	ds_read_b128 v[192:195], v103 offset:46128
	s_waitcnt lgkmcnt(11)
; #define LAS __attribute__((address_space(3)))
; __device__ __forceinline__ unsigned cvt_pk_bf16(float lo, float hi) { unsigned r; asm volatile("v_cvt_pk_bf16_f32 %0, %1, %2" : "=v"(r) : "v"(lo), "v"(hi)); return r; }
; __device__ void phase0(const Params& P, LAS unsigned char* lds, const int G, const int bid) {
;     ...
;               for (int i = 0; i < 4; ++i) { v[i] = v[i] * rstd * w4[i];
;                   u32x2 w; w.x = cvt_pk_bf16(v[i][0], v[i][1]); w.y = cvt_pk_bf16(v[i][2], v[i][3]);
;                   *(u32x2*)(abf + (size_t)row * DM + 4 * lane + 256 * i) = w;
; #pragma unroll
;                   for (int j = 0; j < 4; ++j) { const LAS float* wr_ = wg + (j * 256 + i * 64 + lane) * 20; const float a = v[i][j];
; #pragma unroll
;                       for (int q = 0; q < 4; ++q) { const f32x4 wv = *(const LAS f32x4*)(wr_ + 4 * q);
;                           ga[4 * q] += a * wv[0]; ga[4 * q + 1] += a * wv[1]; ga[4 * q + 2] += a * wv[2]; ga[4 * q + 3] += a * wv[3]; } } }
	v_fmac_f32_e32 v89, v94, v148
	v_fmac_f32_e32 v88, v94, v149
	v_fmac_f32_e32 v85, v94, v150
	v_fmac_f32_e32 v75, v94, v151
	s_waitcnt lgkmcnt(10)
	v_fmac_f32_e32 v74, v94, v140
	v_fmac_f32_e32 v72, v94, v141
	v_fmac_f32_e32 v70, v94, v142
	v_fmac_f32_e32 v67, v94, v143
	s_waitcnt lgkmcnt(9)
	v_fmac_f32_e32 v92, v94, v156
	v_fmac_f32_e32 v90, v94, v157
	v_fmac_f32_e32 v87, v94, v158
	v_fmac_f32_e32 v77, v94, v159
	s_waitcnt lgkmcnt(8)
	v_fmac_f32_e32 v76, v94, v144
	v_fmac_f32_e32 v73, v94, v145
	v_fmac_f32_e32 v71, v94, v146
	v_fmac_f32_e32 v64, v94, v147
	ds_read_b128 v[226:229], v104
	ds_read_b128 v[196:199], v105
	ds_read_b128 v[230:233], v106
	ds_read_b128 v[234:237], v107
	s_waitcnt lgkmcnt(11)
	v_fmac_f32_e32 v89, v95, v170
	v_fmac_f32_e32 v88, v95, v171
	v_fmac_f32_e32 v85, v95, v172
	v_fmac_f32_e32 v75, v95, v173
	ds_read_b128 v[148:151], v102 offset:51200
	s_waitcnt lgkmcnt(11)
	v_fmac_f32_e32 v74, v95, v152
	v_fmac_f32_e32 v72, v95, v153
	v_fmac_f32_e32 v70, v95, v154
	v_fmac_f32_e32 v67, v95, v155
	s_waitcnt lgkmcnt(8)
	v_fmac_f32_e32 v89, v58, v182
	v_fmac_f32_e32 v88, v58, v183
	v_fmac_f32_e32 v85, v58, v184
	v_fmac_f32_e32 v75, v58, v185
	ds_read_b128 v[140:143], v102 offset:51216
	v_fmac_f32_e32 v92, v95, v174
	v_fmac_f32_e32 v90, v95, v175
	v_fmac_f32_e32 v87, v95, v176
	v_fmac_f32_e32 v77, v95, v177
	s_waitcnt lgkmcnt(8)
	v_fmac_f32_e32 v74, v58, v188
	v_fmac_f32_e32 v72, v58, v189
	v_fmac_f32_e32 v70, v58, v190
	v_fmac_f32_e32 v67, v58, v191
	ds_read_b128 v[156:159], v102 offset:51232
	v_fmac_f32_e32 v76, v95, v178
	v_fmac_f32_e32 v73, v95, v179
	v_fmac_f32_e32 v71, v95, v180
	v_fmac_f32_e32 v64, v95, v181
	s_waitcnt lgkmcnt(8)
	v_fmac_f32_e32 v92, v58, v222
	v_fmac_f32_e32 v90, v58, v223
	v_fmac_f32_e32 v87, v58, v224
	v_fmac_f32_e32 v77, v58, v225
	ds_read_b128 v[144:147], v102 offset:51248
	s_waitcnt lgkmcnt(8)
	v_fmac_f32_e32 v76, v58, v192
	v_fmac_f32_e32 v73, v58, v193
	v_fmac_f32_e32 v71, v58, v194
	v_fmac_f32_e32 v64, v58, v195
	ds_read_b128 v[170:173], v103 offset:30720
	s_waitcnt lgkmcnt(8)
	v_fmac_f32_e32 v89, v59, v226
	v_fmac_f32_e32 v88, v59, v227
	v_fmac_f32_e32 v85, v59, v228
	v_fmac_f32_e32 v75, v59, v229
	ds_read_b128 v[152:155], v103 offset:30736
	s_waitcnt lgkmcnt(8)
	v_fmac_f32_e32 v74, v59, v196
	v_fmac_f32_e32 v72, v59, v197
	v_fmac_f32_e32 v70, v59, v198
	v_fmac_f32_e32 v67, v59, v199
	ds_read_b128 v[182:185], v103 offset:30752
	s_waitcnt lgkmcnt(8)
	v_fmac_f32_e32 v92, v59, v230
	v_fmac_f32_e32 v90, v59, v231
	v_fmac_f32_e32 v87, v59, v232
	v_fmac_f32_e32 v77, v59, v233
	ds_read_b128 v[174:177], v103 offset:30768
	s_waitcnt lgkmcnt(8)
	v_fmac_f32_e32 v76, v59, v234
	v_fmac_f32_e32 v73, v59, v235
	v_fmac_f32_e32 v71, v59, v236
	v_fmac_f32_e32 v64, v59, v237
	v_pk_mul_f32 v[58:59], v[54:55], v[66:67] op_sel_hi:[1,0]
	v_pk_mul_f32 v[54:55], v[56:57], v[66:67] op_sel_hi:[1,0]
	v_pk_mul_f32 v[94:95], v[10:11], v[58:59]
	v_pk_mul_f32 v[54:55], v[12:13], v[54:55]
	v_cvt_pk_bf16_f32 v56, v94, v95
	s_nop 0
	v_cvt_pk_bf16_f32 v57, v54, v55
	global_store_dwordx2 v[68:69], v[56:57], off offset:1024
	ds_read_b128 v[188:191], v103 offset:51200
	ds_read_b128 v[178:181], v103 offset:51216
	ds_read_b128 v[222:225], v103 offset:51232
	ds_read_b128 v[192:195], v103 offset:51248
	s_waitcnt lgkmcnt(11)
	v_fmac_f32_e32 v89, v94, v148
	v_fmac_f32_e32 v88, v94, v149
	v_fmac_f32_e32 v85, v94, v150
	v_fmac_f32_e32 v75, v94, v151
	s_waitcnt lgkmcnt(10)
	v_fmac_f32_e32 v74, v94, v140
	v_fmac_f32_e32 v72, v94, v141
	v_fmac_f32_e32 v70, v94, v142
	v_fmac_f32_e32 v67, v94, v143
	s_waitcnt lgkmcnt(9)
	v_fmac_f32_e32 v92, v94, v156
	v_fmac_f32_e32 v90, v94, v157
	v_fmac_f32_e32 v87, v94, v158
	v_fmac_f32_e32 v77, v94, v159
	s_waitcnt lgkmcnt(8)
	v_fmac_f32_e32 v76, v94, v144
	v_fmac_f32_e32 v73, v94, v145
	v_fmac_f32_e32 v71, v94, v146
	v_fmac_f32_e32 v64, v94, v147
	ds_read_b128 v[226:229], v108
	ds_read_b128 v[196:199], v109
	ds_read_b128 v[230:233], v110
	ds_read_b128 v[234:237], v111
	s_waitcnt lgkmcnt(11)
	v_fmac_f32_e32 v89, v95, v170
	v_fmac_f32_e32 v88, v95, v171
	v_fmac_f32_e32 v85, v95, v172
	v_fmac_f32_e32 v75, v95, v173
	ds_read_b128 v[148:151], v102 offset:56320
	s_waitcnt lgkmcnt(11)
	v_fmac_f32_e32 v74, v95, v152
	v_fmac_f32_e32 v72, v95, v153
	v_fmac_f32_e32 v70, v95, v154
	v_fmac_f32_e32 v67, v95, v155
	s_waitcnt lgkmcnt(8)
	v_fmac_f32_e32 v89, v54, v188
	v_fmac_f32_e32 v88, v54, v189
	v_fmac_f32_e32 v85, v54, v190
	v_fmac_f32_e32 v75, v54, v191
	ds_read_b128 v[140:143], v102 offset:56336
	v_fmac_f32_e32 v92, v95, v182
	v_fmac_f32_e32 v90, v95, v183
	v_fmac_f32_e32 v87, v95, v184
	v_fmac_f32_e32 v77, v95, v185
	s_waitcnt lgkmcnt(8)
	v_fmac_f32_e32 v74, v54, v178
	v_fmac_f32_e32 v72, v54, v179
	v_fmac_f32_e32 v70, v54, v180
	v_fmac_f32_e32 v67, v54, v181
	ds_read_b128 v[156:159], v102 offset:56352
	v_fmac_f32_e32 v76, v95, v174
	v_fmac_f32_e32 v73, v95, v175
	v_fmac_f32_e32 v71, v95, v176
	v_fmac_f32_e32 v64, v95, v177
	s_waitcnt lgkmcnt(8)
	v_fmac_f32_e32 v92, v54, v222
	v_fmac_f32_e32 v90, v54, v223
	v_fmac_f32_e32 v87, v54, v224
	v_fmac_f32_e32 v77, v54, v225
	ds_read_b128 v[144:147], v102 offset:56368
	s_waitcnt lgkmcnt(8)
	v_fmac_f32_e32 v76, v54, v192
	v_fmac_f32_e32 v73, v54, v193
	v_fmac_f32_e32 v71, v54, v194
	v_fmac_f32_e32 v64, v54, v195
	ds_read_b128 v[170:173], v103 offset:35840
	s_waitcnt lgkmcnt(8)
	v_fmac_f32_e32 v89, v55, v226
	v_fmac_f32_e32 v88, v55, v227
	v_fmac_f32_e32 v85, v55, v228
	v_fmac_f32_e32 v75, v55, v229
	ds_read_b128 v[152:155], v103 offset:35856
	s_waitcnt lgkmcnt(8)
	v_fmac_f32_e32 v74, v55, v196
	v_fmac_f32_e32 v72, v55, v197
	v_fmac_f32_e32 v70, v55, v198
	v_fmac_f32_e32 v67, v55, v199
	ds_read_b128 v[188:191], v103 offset:35872
	s_waitcnt lgkmcnt(8)
; #define LAS __attribute__((address_space(3)))
; __device__ __forceinline__ unsigned cvt_pk_bf16(float lo, float hi) { unsigned r; asm volatile("v_cvt_pk_bf16_f32 %0, %1, %2" : "=v"(r) : "v"(lo), "v"(hi)); return r; }
; __device__ void phase0(const Params& P, LAS unsigned char* lds, const int G, const int bid) {
;     ...
;               for (int i = 0; i < 4; ++i) { v[i] = v[i] * rstd * w4[i];
;                   u32x2 w; w.x = cvt_pk_bf16(v[i][0], v[i][1]); w.y = cvt_pk_bf16(v[i][2], v[i][3]);
;                   *(u32x2*)(abf + (size_t)row * DM + 4 * lane + 256 * i) = w;
; #pragma unroll
;                   for (int j = 0; j < 4; ++j) { const LAS float* wr_ = wg + (j * 256 + i * 64 + lane) * 20; const float a = v[i][j];
; #pragma unroll
;                       for (int q = 0; q < 4; ++q) { const f32x4 wv = *(const LAS f32x4*)(wr_ + 4 * q);
;                           ga[4 * q] += a * wv[0]; ga[4 * q + 1] += a * wv[1]; ga[4 * q + 2] += a * wv[2]; ga[4 * q + 3] += a * wv[3]; } } }
;               float r8[8], r4[4], r2[2], r1;
; #pragma unroll
;               for (int c = 0; c < 8; ++c) { const bool hi = (lane & 32) != 0; const float send = hi ? ga[c] : ga[c + 8], keep = hi ? ga[c + 8] : ga[c]; r8[c] = keep + __shfl_xor(send, 32); }
; #pragma unroll
;               for (int c = 0; c < 4; ++c) { const bool hi = (lane & 16) != 0; const float send = hi ? r8[c] : r8[c + 4], keep = hi ? r8[c + 4] : r8[c]; r4[c] = keep + __shfl_xor(send, 16); }
; #pragma unroll
;               for (int c = 0; c < 2; ++c) { const bool hi = (lane & 8) != 0; const float send = hi ? r4[c] : r4[c + 2], keep = hi ? r4[c + 2] : r4[c]; r2[c] = keep + __shfl_xor(send, 8); }
;               { const bool hi = (lane & 4) != 0; const float send = hi ? r2[0] : r2[1], keep = hi ? r2[1] : r2[0]; r1 = keep + __shfl_xor(send, 4); }
;               r1 += __shfl_xor(r1, 2); r1 += __shfl_xor(r1, 1);
	v_fmac_f32_e32 v92, v55, v230
	v_fmac_f32_e32 v90, v55, v231
	v_fmac_f32_e32 v87, v55, v232
	v_fmac_f32_e32 v77, v55, v233
	ds_read_b128 v[182:185], v103 offset:35888
	s_waitcnt lgkmcnt(8)
	v_fmac_f32_e32 v76, v55, v234
	v_fmac_f32_e32 v73, v55, v235
	v_fmac_f32_e32 v71, v55, v236
	v_fmac_f32_e32 v64, v55, v237
	v_pk_mul_f32 v[54:55], v[50:51], v[66:67] op_sel_hi:[1,0]
	v_pk_mul_f32 v[50:51], v[52:53], v[66:67] op_sel_hi:[1,0]
	v_pk_mul_f32 v[94:95], v[14:15], v[54:55]
	v_pk_mul_f32 v[50:51], v[16:17], v[50:51]
	v_cvt_pk_bf16_f32 v52, v94, v95
	s_nop 0
	v_cvt_pk_bf16_f32 v53, v50, v51
	global_store_dwordx2 v[68:69], v[52:53], off offset:1536
	ds_read_b128 v[178:181], v103 offset:56320
	ds_read_b128 v[174:177], v103 offset:56336
	ds_read_b128 v[222:225], v103 offset:56352
	ds_read_b128 v[192:195], v103 offset:56368
	s_waitcnt lgkmcnt(11)
	v_fmac_f32_e32 v89, v94, v148
	v_fmac_f32_e32 v88, v94, v149
	v_fmac_f32_e32 v85, v94, v150
	v_fmac_f32_e32 v75, v94, v151
	s_waitcnt lgkmcnt(10)
	v_fmac_f32_e32 v74, v94, v140
	v_fmac_f32_e32 v72, v94, v141
	v_fmac_f32_e32 v70, v94, v142
	v_fmac_f32_e32 v67, v94, v143
	s_waitcnt lgkmcnt(9)
	v_fmac_f32_e32 v92, v94, v156
	v_fmac_f32_e32 v90, v94, v157
	v_fmac_f32_e32 v87, v94, v158
	v_fmac_f32_e32 v77, v94, v159
	s_waitcnt lgkmcnt(8)
	v_fmac_f32_e32 v76, v94, v144
	v_fmac_f32_e32 v73, v94, v145
	v_fmac_f32_e32 v71, v94, v146
	v_fmac_f32_e32 v64, v94, v147
	ds_read_b128 v[226:229], v112
	ds_read_b128 v[196:199], v113
	ds_read_b128 v[230:233], v114
	ds_read_b128 v[234:237], v115
	s_waitcnt lgkmcnt(11)
	v_fmac_f32_e32 v89, v95, v170
	v_fmac_f32_e32 v88, v95, v171
	v_fmac_f32_e32 v85, v95, v172
	v_fmac_f32_e32 v75, v95, v173
	s_waitcnt lgkmcnt(10)
	v_fmac_f32_e32 v74, v95, v152
	v_fmac_f32_e32 v72, v95, v153
	v_fmac_f32_e32 v70, v95, v154
	v_fmac_f32_e32 v67, v95, v155
	s_waitcnt lgkmcnt(7)
	v_fmac_f32_e32 v89, v50, v178
	v_fmac_f32_e32 v88, v50, v179
	v_fmac_f32_e32 v85, v50, v180
	v_fmac_f32_e32 v75, v50, v181
	v_fmac_f32_e32 v92, v95, v188
	v_fmac_f32_e32 v90, v95, v189
	v_fmac_f32_e32 v87, v95, v190
	v_fmac_f32_e32 v77, v95, v191
	s_waitcnt lgkmcnt(6)
	v_fmac_f32_e32 v74, v50, v174
	v_fmac_f32_e32 v72, v50, v175
	v_fmac_f32_e32 v70, v50, v176
	v_fmac_f32_e32 v67, v50, v177
	v_fmac_f32_e32 v76, v95, v182
	v_fmac_f32_e32 v73, v95, v183
	v_fmac_f32_e32 v71, v95, v184
	v_fmac_f32_e32 v64, v95, v185
	s_waitcnt lgkmcnt(5)
	v_fmac_f32_e32 v92, v50, v222
	v_fmac_f32_e32 v90, v50, v223
	v_fmac_f32_e32 v87, v50, v224
	v_fmac_f32_e32 v77, v50, v225
	s_waitcnt lgkmcnt(4)
	v_fmac_f32_e32 v76, v50, v192
	v_fmac_f32_e32 v73, v50, v193
	v_fmac_f32_e32 v71, v50, v194
	v_fmac_f32_e32 v64, v50, v195
	s_waitcnt lgkmcnt(3)
	v_fmac_f32_e32 v89, v51, v226
	v_fmac_f32_e32 v88, v51, v227
	v_fmac_f32_e32 v85, v51, v228
	v_fmac_f32_e32 v75, v51, v229
	s_waitcnt lgkmcnt(2)
	v_fmac_f32_e32 v74, v51, v196
	v_fmac_f32_e32 v72, v51, v197
	v_fmac_f32_e32 v70, v51, v198
	v_fmac_f32_e32 v67, v51, v199
	s_waitcnt lgkmcnt(1)
	v_fmac_f32_e32 v92, v51, v230
	v_fmac_f32_e32 v90, v51, v231
	v_fmac_f32_e32 v87, v51, v232
	v_fmac_f32_e32 v77, v51, v233
	v_cndmask_b32_e32 v50, v89, v92, vcc
	ds_bpermute_b32 v50, v96, v50
	s_waitcnt lgkmcnt(1)
	v_fmac_f32_e32 v76, v51, v234
	v_fmac_f32_e32 v73, v51, v235
	v_fmac_f32_e32 v71, v51, v236
	v_fmac_f32_e32 v64, v51, v237
	v_cndmask_b32_e32 v51, v92, v89, vcc
	s_waitcnt lgkmcnt(0)
	v_add_f32_e32 v50, v51, v50
	v_cndmask_b32_e32 v51, v88, v90, vcc
	ds_bpermute_b32 v51, v96, v51
	v_cndmask_b32_e32 v52, v90, v88, vcc
	v_cndmask_b32_e32 v53, v87, v85, vcc
	v_cndmask_b32_e32 v54, v77, v75, vcc
	v_cndmask_b32_e32 v55, v76, v74, vcc
	s_waitcnt lgkmcnt(0)
	v_add_f32_e32 v51, v52, v51
	v_cndmask_b32_e32 v52, v85, v87, vcc
	ds_bpermute_b32 v52, v96, v52
	v_cndmask_b32_e32 v56, v73, v72, vcc
	v_cndmask_b32_e32 v57, v71, v70, vcc
	v_cndmask_b32_e32 v58, v64, v67, vcc
	s_waitcnt lgkmcnt(0)
	v_add_f32_e32 v52, v53, v52
	v_cndmask_b32_e32 v53, v75, v77, vcc
	ds_bpermute_b32 v53, v96, v53
	s_waitcnt lgkmcnt(0)
	v_add_f32_e32 v53, v54, v53
	v_cndmask_b32_e32 v54, v74, v76, vcc
	ds_bpermute_b32 v54, v96, v54
	s_waitcnt lgkmcnt(0)
	v_add_f32_e32 v54, v55, v54
	v_cndmask_b32_e32 v55, v72, v73, vcc
	ds_bpermute_b32 v55, v96, v55
	s_waitcnt lgkmcnt(0)
	v_add_f32_e32 v55, v56, v55
	v_cndmask_b32_e32 v56, v70, v71, vcc
	ds_bpermute_b32 v56, v96, v56
	s_waitcnt lgkmcnt(0)
	v_add_f32_e32 v56, v57, v56
	v_cndmask_b32_e32 v57, v67, v64, vcc
	ds_bpermute_b32 v57, v96, v57
	s_waitcnt lgkmcnt(0)
	v_add_f32_e32 v57, v58, v57
	v_cndmask_b32_e64 v58, v50, v54, s[42:43]
	v_cndmask_b32_e64 v50, v54, v50, s[42:43]
	ds_bpermute_b32 v54, v97, v58
	s_waitcnt lgkmcnt(0)
	v_add_f32_e32 v50, v50, v54
	v_cndmask_b32_e64 v54, v51, v55, s[42:43]
	ds_bpermute_b32 v54, v97, v54
	v_cndmask_b32_e64 v51, v55, v51, s[42:43]
	s_waitcnt lgkmcnt(0)
	v_add_f32_e32 v51, v51, v54
	v_cndmask_b32_e64 v54, v52, v56, s[42:43]
	ds_bpermute_b32 v54, v97, v54
	v_cndmask_b32_e64 v52, v56, v52, s[42:43]
	s_waitcnt lgkmcnt(0)
	v_add_f32_e32 v52, v52, v54
	v_cndmask_b32_e64 v54, v53, v57, s[42:43]
	ds_bpermute_b32 v54, v97, v54
	v_cndmask_b32_e64 v53, v57, v53, s[42:43]
	s_waitcnt lgkmcnt(0)
	v_add_f32_e32 v53, v53, v54
	v_cndmask_b32_e64 v54, v50, v52, s[44:45]
	v_cndmask_b32_e64 v50, v52, v50, s[44:45]
	ds_bpermute_b32 v52, v98, v54
	s_waitcnt lgkmcnt(0)
	v_add_f32_e32 v50, v50, v52
	v_cndmask_b32_e64 v52, v51, v53, s[44:45]
	ds_bpermute_b32 v52, v98, v52
	v_cndmask_b32_e64 v51, v53, v51, s[44:45]
	s_waitcnt lgkmcnt(0)
	v_add_f32_e32 v51, v51, v52
	v_cndmask_b32_e64 v52, v50, v51, s[46:47]
	v_cndmask_b32_e64 v50, v51, v50, s[46:47]
	ds_bpermute_b32 v51, v99, v52
	s_waitcnt lgkmcnt(0)
	v_add_f32_e32 v50, v50, v51
	ds_bpermute_b32 v51, v100, v50
	s_waitcnt lgkmcnt(0)
	v_add_f32_e32 v50, v50, v51
	ds_bpermute_b32 v51, v101, v50
	s_and_b64 exec, exec, s[48:49]
	s_cbranch_execz .LBB0_1055
; __device__ __forceinline__ float logsigmoidf_(float x) { return fminf(x, 0.0f) - log1pf(__expf(-fabsf(x))); }
; __device__ void phase0(const Params& P, LAS unsigned char* lds, const int G, const int bid) {
;     ...
;               r1 += __shfl_xor(r1, 2); r1 += __shfl_xor(r1, 1);
;               if ((lane & 3) == 0) { float gv = r1 + gbias; if (gcol >= 8) gv = logsigmoidf_(gv); gates[(size_t)row * 16 + gcol] = gv; }
	s_waitcnt lgkmcnt(0)
	v_add_f32_e32 v50, v50, v51
	v_add_f32_e32 v50, v91, v50
	s_and_saveexec_b64 s[8:9], s[40:41]
	s_cbranch_execz .LBB0_1054
	s_mov_b32 s12, 0xbfb8aa3b
	v_mul_f32_e64 v51, |v50|, s12
	v_exp_f32_e32 v64, v51
	v_max_f32_e32 v50, v50, v50
	v_min_f32_e32 v65, 0, v50
	s_mov_b32 s12, 0x3f2aaaab
	v_add_f32_e32 v52, 1.0, v64
	v_add_f32_e32 v50, -1.0, v52
	v_sub_f32_e32 v51, v50, v52
	v_sub_f32_e32 v50, v64, v50
	v_add_f32_e32 v51, 1.0, v51
	v_add_f32_e32 v53, v50, v51
	v_frexp_mant_f32_e32 v54, v52
	v_cvt_f64_f32_e32 v[50:51], v52
	v_frexp_exp_i32_f64_e32 v50, v[50:51]
	v_cmp_gt_f32_e64 s[50:51], s12, v54
	s_mov_b32 s12, 0x3f317218
	s_nop 0
	v_subbrev_co_u32_e64 v58, s[50:51], 0, v50, s[50:51]
	v_sub_u32_e32 v50, 0, v58
	v_ldexp_f32 v51, v52, v50
	v_add_f32_e32 v52, -1.0, v51
	v_add_f32_e32 v54, 1.0, v51
	v_ldexp_f32 v50, v53, v50
	v_add_f32_e32 v53, 1.0, v52
	v_add_f32_e32 v55, -1.0, v54
	v_sub_f32_e32 v53, v51, v53
	v_sub_f32_e32 v51, v51, v55
	v_add_f32_e32 v53, v50, v53
	v_add_f32_e32 v50, v50, v51
	v_add_f32_e32 v59, v54, v50
	v_rcp_f32_e32 v61, v59
	v_sub_f32_e32 v51, v59, v54
	v_sub_f32_e32 v60, v50, v51
	v_add_f32_e32 v51, v52, v53
	v_mul_f32_e32 v63, v51, v61
	v_sub_f32_e32 v50, v51, v52
	v_mul_f32_e32 v52, v59, v63
	v_fma_f32 v54, v63, v59, -v52
	v_fmac_f32_e32 v54, v63, v60
	v_sub_f32_e32 v62, v53, v50
	v_add_f32_e32 v50, v52, v54
	v_sub_f32_e32 v53, v51, v50
	v_pk_add_f32 v[56:57], v[50:51], v[52:53] neg_lo:[0,1] neg_hi:[0,1]
	v_mov_b32_e32 v55, v50
	v_pk_add_f32 v[50:51], v[56:57], v[54:55] neg_lo:[0,1] neg_hi:[0,1]
	s_nop 0
	v_add_f32_e32 v51, v62, v51
	v_add_f32_e32 v50, v50, v51
	v_add_f32_e32 v51, v53, v50
	v_mul_f32_e32 v62, v61, v51
	v_mul_f32_e32 v52, v59, v62
	v_fma_f32 v54, v62, v59, -v52
	v_fmac_f32_e32 v54, v62, v60
	v_sub_f32_e32 v53, v53, v51
	v_add_f32_e32 v59, v50, v53
	v_add_f32_e32 v50, v52, v54
	v_sub_f32_e32 v53, v51, v50
	v_pk_add_f32 v[56:57], v[50:51], v[52:53] neg_lo:[0,1] neg_hi:[0,1]
	v_mov_b32_e32 v55, v50
	v_pk_add_f32 v[50:51], v[56:57], v[54:55] neg_lo:[0,1] neg_hi:[0,1]
	s_nop 0
	v_add_f32_e32 v51, v59, v51
	v_add_f32_e32 v50, v50, v51
	v_add_f32_e32 v51, v63, v62
	v_add_f32_e32 v50, v53, v50
	v_sub_f32_e32 v52, v51, v63
	v_mul_f32_e32 v50, v61, v50
	v_sub_f32_e32 v52, v62, v52
	v_add_f32_e32 v52, v52, v50
	v_add_f32_e32 v54, v51, v52
	v_mul_f32_e32 v55, v54, v54
	v_fmamk_f32 v50, v55, 0x3e9b6dac, v208
	v_fmaak_f32 v169, v55, v50, 0x3f2aaada
	v_cvt_f32_i32_e32 v50, v58
	v_sub_f32_e32 v51, v54, v51
	v_sub_f32_e32 v51, v52, v51
	v_ldexp_f32 v56, v51, 1
	v_mul_f32_e32 v51, v54, v55
	v_ldexp_f32 v53, v54, 1
	v_pk_mul_f32 v[54:55], v[50:51], v[168:169]
	s_nop 0
	v_fma_f32 v52, v50, s12, -v54
	v_fmac_f32_e32 v52, 0xb102e308, v50
	v_pk_add_f32 v[50:51], v[54:55], v[52:53]
	s_mov_b32 s12, 0x7f800000
	v_sub_f32_e32 v53, v51, v53
	v_sub_f32_e32 v53, v55, v53
	v_add_f32_e32 v57, v56, v53
	v_mov_b32_e32 v56, v54
	v_pk_add_f32 v[54:55], v[50:51], v[54:55] neg_lo:[0,1] neg_hi:[0,1]
	v_pk_add_f32 v[58:59], v[50:51], v[56:57]
	v_mov_b32_e32 v53, v50
	v_mov_b32_e32 v55, v59
	v_pk_add_f32 v[60:61], v[52:53], v[54:55] neg_lo:[0,1] neg_hi:[0,1]
	v_pk_add_f32 v[52:53], v[52:53], v[54:55]
	v_mov_b32_e32 v56, v57
	v_pk_add_f32 v[54:55], v[52:53], v[50:51] op_sel:[1,0] op_sel_hi:[0,1] neg_lo:[0,1] neg_hi:[0,1]
	s_nop 0
	v_pk_add_f32 v[62:63], v[58:59], v[54:55] op_sel_hi:[1,0] neg_lo:[0,1] neg_hi:[0,1]
	v_mov_b32_e32 v58, v59
	v_mov_b32_e32 v59, v53
	v_pk_mov_b32 v[54:55], v[50:51], v[54:55] op_sel:[1,0]
	v_mov_b32_e32 v57, v50
	v_pk_add_f32 v[54:55], v[58:59], v[54:55] neg_lo:[0,1] neg_hi:[0,1]
	v_mov_b32_e32 v62, v60
	v_pk_add_f32 v[50:51], v[56:57], v[54:55] neg_lo:[0,1] neg_hi:[0,1]
	v_mov_b32_e32 v61, v53
	v_pk_add_f32 v[54:55], v[62:63], v[50:51]
	v_cmp_neq_f32_e64 s[50:51], s12, v64
	v_pk_add_f32 v[56:57], v[54:55], v[54:55] op_sel:[0,1] op_sel_hi:[1,0]
	s_mov_b32 s12, 0x33800000
	v_pk_add_f32 v[52:53], v[52:53], v[56:57] op_sel:[1,0] op_sel_hi:[0,1]
	s_nop 0
	v_mov_b32_e32 v55, v52
	v_pk_add_f32 v[58:59], v[54:55], v[60:61] neg_lo:[0,1] neg_hi:[0,1]
	v_mov_b32_e32 v51, v56
	v_sub_f32_e32 v53, v54, v58
	v_pk_add_f32 v[50:51], v[50:51], v[58:59] neg_lo:[0,1] neg_hi:[0,1]
	v_sub_f32_e32 v53, v60, v53
	v_add_f32_e32 v50, v50, v53
	v_add_f32_e32 v50, v50, v51
	v_add_f32_e32 v50, v52, v50
	v_cndmask_b32_e64 v50, v212, v50, s[50:51]
	v_cmp_ngt_f32_e64 s[50:51], -1.0, v64
	s_nop 1
	v_cndmask_b32_e64 v50, v213, v50, s[50:51]
	v_cmp_neq_f32_e64 s[50:51], -1.0, v64
	s_nop 1
	v_cndmask_b32_e64 v50, v214, v50, s[50:51]
	v_cmp_lt_f32_e64 s[50:51], |v64|, s12
	s_nop 1
	v_cndmask_b32_e64 v50, v50, v64, s[50:51]
	v_sub_f32_e32 v50, v65, v50

; #define LAS __attribute__((address_space(3)))
; __device__ __forceinline__ unsigned cvt_pk_bf16(float lo, float hi) { unsigned r; asm volatile("v_cvt_pk_bf16_f32 %0, %1, %2" : "=v"(r) : "v"(lo), "v"(hi)); return r; }
; __device__ void phase0(const Params& P, LAS unsigned char* lds, const int G, const int bid) {
;     ...
;           for (int rr = 0; rr < 4; ++rr) { const int row = row0 + rr * G * 8; if (row >= NTOK) continue;
;               f32x4 (&v)[4] = vv[rr]; float ss = 0.f;
; #pragma unroll
;               for (int i = 0; i < 4; ++i)
; #pragma unroll
;                   for (int j = 0; j < 4; ++j) ss += v[i][j] * v[i][j];
; #pragma unroll
;               for (int o = 32; o >= 1; o >>= 1) ss += __shfl_xor(ss, o);
;               const float rstd = rsqrtf(ss * (1.0f / DM) + 1e-6f);
;               float ga[16];
; #pragma unroll
;               for (int c = 0; c < 16; ++c) ga[c] = 0.f;
; #pragma unroll
;               for (int i = 0; i < 4; ++i) { v[i] = v[i] * rstd * w4[i];
;                   u32x2 w; w.x = cvt_pk_bf16(v[i][0], v[i][1]); w.y = cvt_pk_bf16(v[i][2], v[i][3]);
;                   *(u32x2*)(abf + (size_t)row * DM + 4 * lane + 256 * i) = w;
; #pragma unroll
;                   for (int j = 0; j < 4; ++j) { const LAS float* wr_ = wg + (j * 256 + i * 64 + lane) * 20; const float a = v[i][j];
; #pragma unroll
;                       for (int q = 0; q < 4; ++q) { const f32x4 wv = *(const LAS f32x4*)(wr_ + 4 * q);
;                           ga[4 * q] += a * wv[0]; ga[4 * q + 1] += a * wv[1]; ga[4 * q + 2] += a * wv[2]; ga[4 * q + 3] += a * wv[3]; } } }
.LBB0_1055:
	s_or_b64 exec, exec, s[6:7]
	v_cmp_gt_i32_e64 s[50:51], s15, v86
	s_and_saveexec_b64 s[6:7], s[50:51]
	s_cbranch_execz .LBB0_1060
	s_waitcnt vmcnt(11)
	v_mul_f32_e32 v54, v47, v47
	v_fmac_f32_e32 v54, v46, v46
	v_fmac_f32_e32 v54, v48, v48
	v_fmac_f32_e32 v54, v49, v49
	s_waitcnt vmcnt(10)
	v_fmac_f32_e32 v54, v42, v42
	v_fmac_f32_e32 v54, v43, v43
	v_fmac_f32_e32 v54, v44, v44
	v_fmac_f32_e32 v54, v45, v45
	s_waitcnt vmcnt(9)
	v_fmac_f32_e32 v54, v38, v38
	v_fmac_f32_e32 v54, v39, v39
	v_fmac_f32_e32 v54, v40, v40
	v_fmac_f32_e32 v54, v41, v41
	s_waitcnt vmcnt(8)
	v_pk_mul_f32 v[52:53], v[34:35], v[34:35]
	s_waitcnt lgkmcnt(0)
	v_pk_mul_f32 v[50:51], v[36:37], v[36:37]
	v_add_f32_e32 v52, v52, v54
	v_add_f32_e32 v52, v53, v52
	v_add_f32_e32 v50, v50, v52
	v_add_f32_e32 v50, v51, v50
	ds_bpermute_b32 v51, v96, v50
	v_ashrrev_i32_e32 v87, 31, v86
	v_lshlrev_b64 v[52:53], 11, v[86:87]
	v_lshl_add_u64 v[52:53], v[80:81], 0, v[52:53]
	s_waitcnt lgkmcnt(0)
	v_add_f32_e32 v50, v50, v51
	ds_bpermute_b32 v51, v97, v50
	s_waitcnt lgkmcnt(0)
	v_add_f32_e32 v50, v50, v51
	ds_bpermute_b32 v51, v98, v50
	s_waitcnt lgkmcnt(0)
	v_add_f32_e32 v50, v50, v51
	ds_bpermute_b32 v51, v99, v50
	s_waitcnt lgkmcnt(0)
	v_add_f32_e32 v50, v50, v51
	ds_bpermute_b32 v51, v100, v50
	s_waitcnt lgkmcnt(0)
	v_add_f32_e32 v50, v50, v51
	ds_bpermute_b32 v51, v101, v50
	s_waitcnt lgkmcnt(0)
	v_add_f32_e32 v50, v50, v51
	v_fmamk_f32 v50, v50, 0x3a800000, v210
	v_cmp_gt_f32_e64 s[50:51], s30, v50
	v_mul_f32_e32 v51, 0x4b800000, v50
	s_nop 0
	v_cndmask_b32_e64 v50, v50, v51, s[50:51]
	v_rsq_f32_e32 v50, v50
	s_nop 0
	v_mul_f32_e32 v51, 0x45800000, v50
	v_cndmask_b32_e64 v50, v50, v51, s[50:51]
	v_pk_mul_f32 v[54:55], v[46:47], v[50:51] op_sel_hi:[1,0]
	v_pk_mul_f32 v[46:47], v[48:49], v[50:51] op_sel_hi:[1,0]
	v_pk_mul_f32 v[48:49], v[2:3], v[54:55]
	v_pk_mul_f32 v[46:47], v[4:5], v[46:47]
	v_cvt_pk_bf16_f32 v54, v48, v49
	s_nop 0
	v_cvt_pk_bf16_f32 v55, v46, v47
	global_store_dwordx2 v[52:53], v[54:55], off
	ds_read_b128 v[140:143], v102 offset:40960
	ds_read_b128 v[144:147], v102 offset:40976
	ds_read_b128 v[148:151], v102 offset:40992
	ds_read_b128 v[152:155], v102 offset:41008
	ds_read_b128 v[156:159], v102 offset:61440
	ds_read_b128 v[170:173], v102 offset:61456
	ds_read_b128 v[174:177], v102 offset:61472
	ds_read_b128 v[178:181], v102 offset:61488
	ds_read_b128 v[182:185], v103 offset:40960
	ds_read_b128 v[188:191], v103 offset:40976
	ds_read_b128 v[192:195], v103 offset:40992
	ds_read_b128 v[196:199], v103 offset:41008
	s_waitcnt lgkmcnt(11)
	v_fma_f32 v65, v140, v48, 0
	v_fma_f32 v62, v142, v48, 0
	s_waitcnt lgkmcnt(10)
	v_fma_f32 v58, v144, v48, 0
	v_fma_f32 v56, v145, v48, 0
	v_fma_f32 v54, v146, v48, 0
	v_fma_f32 v51, v147, v48, 0
	s_waitcnt lgkmcnt(9)
	v_fma_f32 v67, v148, v48, 0
	v_fma_f32 v66, v149, v48, 0
	ds_read_b128 v[222:225], v103 offset:61440
	v_fma_f32 v64, v141, v48, 0
	v_fma_f32 v59, v143, v48, 0
	v_fma_f32 v63, v150, v48, 0
	v_fma_f32 v61, v151, v48, 0
	s_waitcnt lgkmcnt(8)
	v_fmac_f32_e32 v65, v156, v49
	v_fmac_f32_e32 v64, v157, v49
	v_fmac_f32_e32 v62, v158, v49
	v_fmac_f32_e32 v59, v159, v49
	ds_read_b128 v[226:229], v103 offset:61456
	v_fma_f32 v60, v152, v48, 0
	v_fma_f32 v57, v153, v48, 0
	v_fma_f32 v55, v154, v48, 0
	v_fma_f32 v48, v155, v48, 0
	s_waitcnt lgkmcnt(8)
	v_fmac_f32_e32 v58, v170, v49
	v_fmac_f32_e32 v56, v171, v49
	v_fmac_f32_e32 v54, v172, v49
	v_fmac_f32_e32 v51, v173, v49
	ds_read_b128 v[230:233], v103 offset:61472
	s_waitcnt lgkmcnt(8)
	v_fmac_f32_e32 v67, v174, v49
	v_fmac_f32_e32 v66, v175, v49
	v_fmac_f32_e32 v63, v176, v49
	v_fmac_f32_e32 v61, v177, v49
	ds_read_b128 v[234:237], v103 offset:61488
	s_waitcnt lgkmcnt(8)
	v_fmac_f32_e32 v60, v178, v49
	v_fmac_f32_e32 v57, v179, v49
	v_fmac_f32_e32 v55, v180, v49
	v_fmac_f32_e32 v48, v181, v49
	ds_read_b128 v[144:147], v102 offset:46080
	ds_read_b128 v[140:143], v102 offset:46096
	ds_read_b128 v[148:151], v102 offset:46112
	ds_read_b128 v[156:159], v102 offset:46128
	s_waitcnt lgkmcnt(11)
	v_fmac_f32_e32 v65, v182, v46
	v_fmac_f32_e32 v64, v183, v46
	v_fmac_f32_e32 v62, v184, v46
	v_fmac_f32_e32 v59, v185, v46
	ds_read_b128 v[152:155], v103 offset:25600
	s_waitcnt lgkmcnt(11)
	v_fmac_f32_e32 v58, v46, v188
	v_fmac_f32_e32 v56, v46, v189
	v_fmac_f32_e32 v54, v46, v190
	v_fmac_f32_e32 v51, v46, v191
	s_waitcnt lgkmcnt(8)
	v_fmac_f32_e32 v65, v47, v222
	v_fmac_f32_e32 v64, v47, v223
	v_fmac_f32_e32 v62, v47, v224
	v_fmac_f32_e32 v59, v47, v225
	ds_read_b128 v[170:173], v103 offset:25616
	v_fmac_f32_e32 v67, v46, v192
	v_fmac_f32_e32 v66, v46, v193
	v_fmac_f32_e32 v63, v46, v194
	v_fmac_f32_e32 v61, v46, v195
	s_waitcnt lgkmcnt(8)
	v_fmac_f32_e32 v58, v47, v226
	v_fmac_f32_e32 v56, v47, v227
	v_fmac_f32_e32 v54, v47, v228
	v_fmac_f32_e32 v51, v47, v229
	ds_read_b128 v[174:177], v103 offset:25632
	v_fmac_f32_e32 v60, v46, v196
	v_fmac_f32_e32 v57, v46, v197
	v_fmac_f32_e32 v55, v46, v198
	v_fmac_f32_e32 v48, v46, v199
	s_waitcnt lgkmcnt(8)
	v_fmac_f32_e32 v67, v47, v230
	v_fmac_f32_e32 v66, v47, v231
	v_fmac_f32_e32 v63, v47, v232
	v_fmac_f32_e32 v61, v47, v233
	ds_read_b128 v[178:181], v103 offset:25648
	s_waitcnt lgkmcnt(8)
	v_fmac_f32_e32 v60, v47, v234
	v_fmac_f32_e32 v57, v47, v235
	v_fmac_f32_e32 v55, v47, v236
	v_fmac_f32_e32 v48, v47, v237
	v_pk_mul_f32 v[46:47], v[42:43], v[50:51] op_sel_hi:[1,0]
	v_pk_mul_f32 v[42:43], v[44:45], v[50:51] op_sel_hi:[1,0]
	v_pk_mul_f32 v[76:77], v[6:7], v[46:47]
	v_pk_mul_f32 v[42:43], v[8:9], v[42:43]
	v_cvt_pk_bf16_f32 v44, v76, v77
	s_nop 0
	v_cvt_pk_bf16_f32 v45, v42, v43
	global_store_dwordx2 v[52:53], v[44:45], off offset:512
	ds_read_b128 v[182:185], v103 offset:46080
	ds_read_b128 v[188:191], v103 offset:46096
	ds_read_b128 v[222:225], v103 offset:46112
	ds_read_b128 v[192:195], v103 offset:46128
	s_waitcnt lgkmcnt(11)
; #define LAS __attribute__((address_space(3)))
; __device__ __forceinline__ unsigned cvt_pk_bf16(float lo, float hi) { unsigned r; asm volatile("v_cvt_pk_bf16_f32 %0, %1, %2" : "=v"(r) : "v"(lo), "v"(hi)); return r; }
; __device__ void phase0(const Params& P, LAS unsigned char* lds, const int G, const int bid) {
;     ...
;               for (int i = 0; i < 4; ++i) { v[i] = v[i] * rstd * w4[i];
;                   u32x2 w; w.x = cvt_pk_bf16(v[i][0], v[i][1]); w.y = cvt_pk_bf16(v[i][2], v[i][3]);
;                   *(u32x2*)(abf + (size_t)row * DM + 4 * lane + 256 * i) = w;
; #pragma unroll
;                   for (int j = 0; j < 4; ++j) { const LAS float* wr_ = wg + (j * 256 + i * 64 + lane) * 20; const float a = v[i][j];
; #pragma unroll
;                       for (int q = 0; q < 4; ++q) { const f32x4 wv = *(const LAS f32x4*)(wr_ + 4 * q);
;                           ga[4 * q] += a * wv[0]; ga[4 * q + 1] += a * wv[1]; ga[4 * q + 2] += a * wv[2]; ga[4 * q + 3] += a * wv[3]; } } }
	v_fmac_f32_e32 v65, v76, v144
	v_fmac_f32_e32 v64, v76, v145
	v_fmac_f32_e32 v62, v76, v146
	v_fmac_f32_e32 v59, v76, v147
	s_waitcnt lgkmcnt(10)
	v_fmac_f32_e32 v58, v76, v140
	v_fmac_f32_e32 v56, v76, v141
	v_fmac_f32_e32 v54, v76, v142
	v_fmac_f32_e32 v51, v76, v143
	s_waitcnt lgkmcnt(9)
	v_fmac_f32_e32 v67, v76, v148
	v_fmac_f32_e32 v66, v76, v149
	v_fmac_f32_e32 v63, v76, v150
	v_fmac_f32_e32 v61, v76, v151
	s_waitcnt lgkmcnt(8)
	v_fmac_f32_e32 v60, v76, v156
	v_fmac_f32_e32 v57, v76, v157
	v_fmac_f32_e32 v55, v76, v158
	v_fmac_f32_e32 v48, v76, v159
	ds_read_b128 v[226:229], v104
	ds_read_b128 v[196:199], v105
	ds_read_b128 v[230:233], v106
	ds_read_b128 v[234:237], v107
	s_waitcnt lgkmcnt(11)
	v_fmac_f32_e32 v65, v77, v152
	v_fmac_f32_e32 v64, v77, v153
	v_fmac_f32_e32 v62, v77, v154
	v_fmac_f32_e32 v59, v77, v155
	ds_read_b128 v[144:147], v102 offset:51200
	s_waitcnt lgkmcnt(11)
	v_fmac_f32_e32 v58, v77, v170
	v_fmac_f32_e32 v56, v77, v171
	v_fmac_f32_e32 v54, v77, v172
	v_fmac_f32_e32 v51, v77, v173
	s_waitcnt lgkmcnt(8)
	v_fmac_f32_e32 v65, v42, v182
	v_fmac_f32_e32 v64, v42, v183
	v_fmac_f32_e32 v62, v42, v184
	v_fmac_f32_e32 v59, v42, v185
	ds_read_b128 v[140:143], v102 offset:51216
	v_fmac_f32_e32 v67, v77, v174
	v_fmac_f32_e32 v66, v77, v175
	v_fmac_f32_e32 v63, v77, v176
	v_fmac_f32_e32 v61, v77, v177
	s_waitcnt lgkmcnt(8)
	v_fmac_f32_e32 v58, v42, v188
	v_fmac_f32_e32 v56, v42, v189
	v_fmac_f32_e32 v54, v42, v190
	v_fmac_f32_e32 v51, v42, v191
	ds_read_b128 v[148:151], v102 offset:51232
	v_fmac_f32_e32 v60, v77, v178
	v_fmac_f32_e32 v57, v77, v179
	v_fmac_f32_e32 v55, v77, v180
	v_fmac_f32_e32 v48, v77, v181
	s_waitcnt lgkmcnt(8)
	v_fmac_f32_e32 v67, v42, v222
	v_fmac_f32_e32 v66, v42, v223
	v_fmac_f32_e32 v63, v42, v224
	v_fmac_f32_e32 v61, v42, v225
	ds_read_b128 v[156:159], v102 offset:51248
	s_waitcnt lgkmcnt(8)
	v_fmac_f32_e32 v60, v42, v192
	v_fmac_f32_e32 v57, v42, v193
	v_fmac_f32_e32 v55, v42, v194
	v_fmac_f32_e32 v48, v42, v195
	ds_read_b128 v[152:155], v103 offset:30720
	s_waitcnt lgkmcnt(8)
	v_fmac_f32_e32 v65, v43, v226
	v_fmac_f32_e32 v64, v43, v227
	v_fmac_f32_e32 v62, v43, v228
	v_fmac_f32_e32 v59, v43, v229
	ds_read_b128 v[170:173], v103 offset:30736
	s_waitcnt lgkmcnt(8)
	v_fmac_f32_e32 v58, v43, v196
	v_fmac_f32_e32 v56, v43, v197
	v_fmac_f32_e32 v54, v43, v198
	v_fmac_f32_e32 v51, v43, v199
	ds_read_b128 v[182:185], v103 offset:30752
	s_waitcnt lgkmcnt(8)
	v_fmac_f32_e32 v67, v43, v230
	v_fmac_f32_e32 v66, v43, v231
	v_fmac_f32_e32 v63, v43, v232
	v_fmac_f32_e32 v61, v43, v233
	ds_read_b128 v[174:177], v103 offset:30768
	s_waitcnt lgkmcnt(8)
	v_fmac_f32_e32 v60, v43, v234
	v_fmac_f32_e32 v57, v43, v235
	v_fmac_f32_e32 v55, v43, v236
	v_fmac_f32_e32 v48, v43, v237
	v_pk_mul_f32 v[42:43], v[38:39], v[50:51] op_sel_hi:[1,0]
	v_pk_mul_f32 v[38:39], v[40:41], v[50:51] op_sel_hi:[1,0]
	v_pk_mul_f32 v[76:77], v[10:11], v[42:43]
	v_pk_mul_f32 v[38:39], v[12:13], v[38:39]
	v_cvt_pk_bf16_f32 v40, v76, v77
	s_nop 0
	v_cvt_pk_bf16_f32 v41, v38, v39
	global_store_dwordx2 v[52:53], v[40:41], off offset:1024
	ds_read_b128 v[188:191], v103 offset:51200
	ds_read_b128 v[178:181], v103 offset:51216
	ds_read_b128 v[222:225], v103 offset:51232
	ds_read_b128 v[192:195], v103 offset:51248
	s_waitcnt lgkmcnt(11)
	v_fmac_f32_e32 v65, v76, v144
	v_fmac_f32_e32 v64, v76, v145
	v_fmac_f32_e32 v62, v76, v146
	v_fmac_f32_e32 v59, v76, v147
	s_waitcnt lgkmcnt(10)
	v_fmac_f32_e32 v58, v76, v140
	v_fmac_f32_e32 v56, v76, v141
	v_fmac_f32_e32 v54, v76, v142
	v_fmac_f32_e32 v51, v76, v143
	s_waitcnt lgkmcnt(9)
	v_fmac_f32_e32 v67, v76, v148
	v_fmac_f32_e32 v66, v76, v149
	v_fmac_f32_e32 v63, v76, v150
	v_fmac_f32_e32 v61, v76, v151
	s_waitcnt lgkmcnt(8)
	v_fmac_f32_e32 v60, v76, v156
	v_fmac_f32_e32 v57, v76, v157
	v_fmac_f32_e32 v55, v76, v158
	v_fmac_f32_e32 v48, v76, v159
	ds_read_b128 v[226:229], v108
	ds_read_b128 v[196:199], v109
	ds_read_b128 v[230:233], v110
	ds_read_b128 v[234:237], v111
	s_waitcnt lgkmcnt(11)
	v_fmac_f32_e32 v65, v77, v152
	v_fmac_f32_e32 v64, v77, v153
	v_fmac_f32_e32 v62, v77, v154
	v_fmac_f32_e32 v59, v77, v155
	ds_read_b128 v[144:147], v102 offset:56320
	s_waitcnt lgkmcnt(11)
	v_fmac_f32_e32 v58, v77, v170
	v_fmac_f32_e32 v56, v77, v171
	v_fmac_f32_e32 v54, v77, v172
	v_fmac_f32_e32 v51, v77, v173
	s_waitcnt lgkmcnt(8)
	v_fmac_f32_e32 v65, v38, v188
	v_fmac_f32_e32 v64, v38, v189
	v_fmac_f32_e32 v62, v38, v190
	v_fmac_f32_e32 v59, v38, v191
	ds_read_b128 v[140:143], v102 offset:56336
	v_fmac_f32_e32 v67, v77, v182
	v_fmac_f32_e32 v66, v77, v183
	v_fmac_f32_e32 v63, v77, v184
	v_fmac_f32_e32 v61, v77, v185
	s_waitcnt lgkmcnt(8)
	v_fmac_f32_e32 v58, v38, v178
	v_fmac_f32_e32 v56, v38, v179
	v_fmac_f32_e32 v54, v38, v180
	v_fmac_f32_e32 v51, v38, v181
	ds_read_b128 v[148:151], v102 offset:56352
	v_fmac_f32_e32 v60, v77, v174
	v_fmac_f32_e32 v57, v77, v175
	v_fmac_f32_e32 v55, v77, v176
	v_fmac_f32_e32 v48, v77, v177
	s_waitcnt lgkmcnt(8)
	v_fmac_f32_e32 v67, v38, v222
	v_fmac_f32_e32 v66, v38, v223
	v_fmac_f32_e32 v63, v38, v224
	v_fmac_f32_e32 v61, v38, v225
	ds_read_b128 v[156:159], v102 offset:56368
	s_waitcnt lgkmcnt(8)
	v_fmac_f32_e32 v60, v38, v192
	v_fmac_f32_e32 v57, v38, v193
	v_fmac_f32_e32 v55, v38, v194
	v_fmac_f32_e32 v48, v38, v195
	ds_read_b128 v[152:155], v103 offset:35840
	s_waitcnt lgkmcnt(8)
	v_fmac_f32_e32 v65, v39, v226
	v_fmac_f32_e32 v64, v39, v227
	v_fmac_f32_e32 v62, v39, v228
	v_fmac_f32_e32 v59, v39, v229
	ds_read_b128 v[170:173], v103 offset:35856
	s_waitcnt lgkmcnt(8)
	v_fmac_f32_e32 v58, v39, v196
	v_fmac_f32_e32 v56, v39, v197
	v_fmac_f32_e32 v54, v39, v198
	v_fmac_f32_e32 v51, v39, v199
	ds_read_b128 v[188:191], v103 offset:35872
	s_waitcnt lgkmcnt(8)
; #define LAS __attribute__((address_space(3)))
; __device__ void phase0(const Params& P, LAS unsigned char* lds, const int G, const int bid) {
;     ...
;                   for (int j = 0; j < 4; ++j) { const LAS float* wr_ = wg + (j * 256 + i * 64 + lane) * 20; const float a = v[i][j];
; #pragma unroll
;                       for (int q = 0; q < 4; ++q) { const f32x4 wv = *(const LAS f32x4*)(wr_ + 4 * q);
;                           ga[4 * q] += a * wv[0]; ga[4 * q + 1] += a * wv[1]; ga[4 * q + 2] += a * wv[2]; ga[4 * q + 3] += a * wv[3]; } } }
;               float r8[8], r4[4], r2[2], r1;
; #pragma unroll
;               for (int c = 0; c < 8; ++c) { const bool hi = (lane & 32) != 0; const float send = hi ? ga[c] : ga[c + 8], keep = hi ? ga[c + 8] : ga[c]; r8[c] = keep + __shfl_xor(send, 32); }
; #pragma unroll
;               for (int c = 0; c < 4; ++c) { const bool hi = (lane & 16) != 0; const float send = hi ? r8[c] : r8[c + 4], keep = hi ? r8[c + 4] : r8[c]; r4[c] = keep + __shfl_xor(send, 16); }
; #pragma unroll
;               for (int c = 0; c < 2; ++c) { const bool hi = (lane & 8) != 0; const float send = hi ? r4[c] : r4[c + 2], keep = hi ? r4[c + 2] : r4[c]; r2[c] = keep + __shfl_xor(send, 8); }
;               { const bool hi = (lane & 4) != 0; const float send = hi ? r2[0] : r2[1], keep = hi ? r2[1] : r2[0]; r1 = keep + __shfl_xor(send, 4); }
;               r1 += __shfl_xor(r1, 2); r1 += __shfl_xor(r1, 1);
	v_fmac_f32_e32 v67, v39, v230
	v_fmac_f32_e32 v66, v39, v231
	v_fmac_f32_e32 v63, v39, v232
	v_fmac_f32_e32 v61, v39, v233
	ds_read_b128 v[182:185], v103 offset:35888
	s_waitcnt lgkmcnt(8)
	v_fmac_f32_e32 v60, v39, v234
	v_fmac_f32_e32 v57, v39, v235
	v_fmac_f32_e32 v55, v39, v236
	v_fmac_f32_e32 v48, v39, v237
	v_pk_mul_f32 v[38:39], v[34:35], v[50:51] op_sel_hi:[1,0]
	v_pk_mul_f32 v[34:35], v[36:37], v[50:51] op_sel_hi:[1,0]
	v_pk_mul_f32 v[72:73], v[14:15], v[38:39]
	v_pk_mul_f32 v[34:35], v[16:17], v[34:35]
	v_cvt_pk_bf16_f32 v36, v72, v73
	s_nop 0
	v_cvt_pk_bf16_f32 v37, v34, v35
	global_store_dwordx2 v[52:53], v[36:37], off offset:1536
	ds_read_b128 v[178:181], v103 offset:56320
	ds_read_b128 v[174:177], v103 offset:56336
	ds_read_b128 v[222:225], v103 offset:56352
	ds_read_b128 v[192:195], v103 offset:56368
	s_waitcnt lgkmcnt(11)
	v_fmac_f32_e32 v65, v72, v144
	v_fmac_f32_e32 v64, v72, v145
	v_fmac_f32_e32 v62, v72, v146
	v_fmac_f32_e32 v59, v72, v147
	s_waitcnt lgkmcnt(10)
	v_fmac_f32_e32 v58, v72, v140
	v_fmac_f32_e32 v56, v72, v141
	v_fmac_f32_e32 v54, v72, v142
	v_fmac_f32_e32 v51, v72, v143
	s_waitcnt lgkmcnt(9)
	v_fmac_f32_e32 v67, v72, v148
	v_fmac_f32_e32 v66, v72, v149
	v_fmac_f32_e32 v63, v72, v150
	v_fmac_f32_e32 v61, v72, v151
	s_waitcnt lgkmcnt(8)
	v_fmac_f32_e32 v60, v72, v156
	v_fmac_f32_e32 v57, v72, v157
	v_fmac_f32_e32 v55, v72, v158
	v_fmac_f32_e32 v48, v72, v159
	ds_read_b128 v[226:229], v112
	ds_read_b128 v[196:199], v113
	ds_read_b128 v[230:233], v114
	ds_read_b128 v[234:237], v115
	s_waitcnt lgkmcnt(11)
	v_fmac_f32_e32 v65, v73, v152
	v_fmac_f32_e32 v64, v73, v153
	v_fmac_f32_e32 v62, v73, v154
	v_fmac_f32_e32 v59, v73, v155
	s_waitcnt lgkmcnt(10)
	v_fmac_f32_e32 v58, v73, v170
	v_fmac_f32_e32 v56, v73, v171
	v_fmac_f32_e32 v54, v73, v172
	v_fmac_f32_e32 v51, v73, v173
	s_waitcnt lgkmcnt(7)
	v_fmac_f32_e32 v65, v34, v178
	v_fmac_f32_e32 v64, v34, v179
	v_fmac_f32_e32 v62, v34, v180
	v_fmac_f32_e32 v59, v34, v181
	v_fmac_f32_e32 v67, v73, v188
	v_fmac_f32_e32 v66, v73, v189
	v_fmac_f32_e32 v63, v73, v190
	v_fmac_f32_e32 v61, v73, v191
	s_waitcnt lgkmcnt(6)
	v_fmac_f32_e32 v58, v34, v174
	v_fmac_f32_e32 v56, v34, v175
	v_fmac_f32_e32 v54, v34, v176
	v_fmac_f32_e32 v51, v34, v177
	v_fmac_f32_e32 v60, v73, v182
	v_fmac_f32_e32 v57, v73, v183
	v_fmac_f32_e32 v55, v73, v184
	v_fmac_f32_e32 v48, v73, v185
	s_waitcnt lgkmcnt(5)
	v_fmac_f32_e32 v67, v34, v222
	v_fmac_f32_e32 v66, v34, v223
	v_fmac_f32_e32 v63, v34, v224
	v_fmac_f32_e32 v61, v34, v225
	s_waitcnt lgkmcnt(4)
	v_fmac_f32_e32 v60, v34, v192
	v_fmac_f32_e32 v57, v34, v193
	v_fmac_f32_e32 v55, v34, v194
	v_fmac_f32_e32 v48, v34, v195
	s_waitcnt lgkmcnt(3)
	v_fmac_f32_e32 v65, v35, v226
	v_fmac_f32_e32 v64, v35, v227
	v_fmac_f32_e32 v62, v35, v228
	v_fmac_f32_e32 v59, v35, v229
	s_waitcnt lgkmcnt(2)
	v_fmac_f32_e32 v58, v35, v196
	v_fmac_f32_e32 v56, v35, v197
	v_fmac_f32_e32 v54, v35, v198
	v_fmac_f32_e32 v51, v35, v199
	s_waitcnt lgkmcnt(1)
	v_fmac_f32_e32 v67, v35, v230
	v_fmac_f32_e32 v66, v35, v231
	v_fmac_f32_e32 v63, v35, v232
	v_fmac_f32_e32 v61, v35, v233
	v_cndmask_b32_e32 v34, v65, v67, vcc
	ds_bpermute_b32 v34, v96, v34
	s_waitcnt lgkmcnt(1)
	v_fmac_f32_e32 v60, v35, v234
	v_fmac_f32_e32 v57, v35, v235
	v_fmac_f32_e32 v55, v35, v236
	v_fmac_f32_e32 v48, v35, v237
	v_cndmask_b32_e32 v35, v67, v65, vcc
	s_waitcnt lgkmcnt(0)
	v_add_f32_e32 v34, v35, v34
	v_cndmask_b32_e32 v35, v64, v66, vcc
	ds_bpermute_b32 v35, v96, v35
	v_cndmask_b32_e32 v36, v66, v64, vcc
	v_cndmask_b32_e32 v37, v63, v62, vcc
	v_cndmask_b32_e32 v38, v61, v59, vcc
	v_cndmask_b32_e32 v39, v60, v58, vcc
	s_waitcnt lgkmcnt(0)
	v_add_f32_e32 v35, v36, v35
	v_cndmask_b32_e32 v36, v62, v63, vcc
	ds_bpermute_b32 v36, v96, v36
	v_cndmask_b32_e32 v40, v57, v56, vcc
	v_cndmask_b32_e32 v41, v55, v54, vcc
	v_cndmask_b32_e32 v42, v48, v51, vcc
	s_waitcnt lgkmcnt(0)
	v_add_f32_e32 v36, v37, v36
	v_cndmask_b32_e32 v37, v59, v61, vcc
	ds_bpermute_b32 v37, v96, v37
	s_waitcnt lgkmcnt(0)
	v_add_f32_e32 v37, v38, v37
	v_cndmask_b32_e32 v38, v58, v60, vcc
	ds_bpermute_b32 v38, v96, v38
	s_waitcnt lgkmcnt(0)
	v_add_f32_e32 v38, v39, v38
	v_cndmask_b32_e32 v39, v56, v57, vcc
	ds_bpermute_b32 v39, v96, v39
	s_waitcnt lgkmcnt(0)
	v_add_f32_e32 v39, v40, v39
	v_cndmask_b32_e32 v40, v54, v55, vcc
	ds_bpermute_b32 v40, v96, v40
	s_waitcnt lgkmcnt(0)
	v_add_f32_e32 v40, v41, v40
	v_cndmask_b32_e32 v41, v51, v48, vcc
	ds_bpermute_b32 v41, v96, v41
	s_waitcnt lgkmcnt(0)
	v_add_f32_e32 v41, v42, v41
	v_cndmask_b32_e64 v42, v34, v38, s[42:43]
	v_cndmask_b32_e64 v34, v38, v34, s[42:43]
	ds_bpermute_b32 v38, v97, v42
	s_waitcnt lgkmcnt(0)
	v_add_f32_e32 v34, v34, v38
	v_cndmask_b32_e64 v38, v35, v39, s[42:43]
	ds_bpermute_b32 v38, v97, v38
	v_cndmask_b32_e64 v35, v39, v35, s[42:43]
	s_waitcnt lgkmcnt(0)
	v_add_f32_e32 v35, v35, v38
	v_cndmask_b32_e64 v38, v36, v40, s[42:43]
	ds_bpermute_b32 v38, v97, v38
	v_cndmask_b32_e64 v36, v40, v36, s[42:43]
	s_waitcnt lgkmcnt(0)
	v_add_f32_e32 v36, v36, v38
	v_cndmask_b32_e64 v38, v37, v41, s[42:43]
	ds_bpermute_b32 v38, v97, v38
	v_cndmask_b32_e64 v37, v41, v37, s[42:43]
	s_waitcnt lgkmcnt(0)
	v_add_f32_e32 v37, v37, v38
	v_cndmask_b32_e64 v38, v34, v36, s[44:45]
	v_cndmask_b32_e64 v34, v36, v34, s[44:45]
	ds_bpermute_b32 v36, v98, v38
	s_waitcnt lgkmcnt(0)
	v_add_f32_e32 v34, v34, v36
	v_cndmask_b32_e64 v36, v35, v37, s[44:45]
	ds_bpermute_b32 v36, v98, v36
	v_cndmask_b32_e64 v35, v37, v35, s[44:45]
	s_waitcnt lgkmcnt(0)
	v_add_f32_e32 v35, v35, v36
	v_cndmask_b32_e64 v36, v34, v35, s[46:47]
	v_cndmask_b32_e64 v34, v35, v34, s[46:47]
	ds_bpermute_b32 v35, v99, v36
	s_waitcnt lgkmcnt(0)
	v_add_f32_e32 v34, v34, v35
	ds_bpermute_b32 v35, v100, v34
	s_waitcnt lgkmcnt(0)
	v_add_f32_e32 v34, v34, v35
	ds_bpermute_b32 v35, v101, v34
	s_and_b64 exec, exec, s[48:49]
	s_cbranch_execz .LBB0_1060
; __device__ __forceinline__ float logsigmoidf_(float x) { return fminf(x, 0.0f) - log1pf(__expf(-fabsf(x))); }
; __device__ void phase0(const Params& P, LAS unsigned char* lds, const int G, const int bid) {
;     ...
;               if ((lane & 3) == 0) { float gv = r1 + gbias; if (gcol >= 8) gv = logsigmoidf_(gv); gates[(size_t)row * 16 + gcol] = gv; }
	s_waitcnt lgkmcnt(0)
	v_add_f32_e32 v34, v34, v35
	v_add_f32_e32 v34, v91, v34
	s_and_saveexec_b64 s[8:9], s[40:41]
	s_cbranch_execz .LBB0_1059
	s_mov_b32 s12, 0xbfb8aa3b
	v_mul_f32_e64 v35, |v34|, s12
	v_exp_f32_e32 v48, v35
	v_max_f32_e32 v34, v34, v34
	v_min_f32_e32 v49, 0, v34
	s_mov_b32 s12, 0x3f2aaaab
	v_add_f32_e32 v36, 1.0, v48
	v_add_f32_e32 v34, -1.0, v36
	v_sub_f32_e32 v35, v34, v36
	v_sub_f32_e32 v34, v48, v34
	v_add_f32_e32 v35, 1.0, v35
	v_add_f32_e32 v37, v34, v35
	v_frexp_mant_f32_e32 v38, v36
	v_cvt_f64_f32_e32 v[34:35], v36
	v_frexp_exp_i32_f64_e32 v34, v[34:35]
	v_cmp_gt_f32_e64 s[50:51], s12, v38
	s_mov_b32 s12, 0x3f317218
	s_nop 0
	v_subbrev_co_u32_e64 v42, s[50:51], 0, v34, s[50:51]
	v_sub_u32_e32 v34, 0, v42
	v_ldexp_f32 v35, v36, v34
	v_add_f32_e32 v36, -1.0, v35
	v_add_f32_e32 v38, 1.0, v35
	v_ldexp_f32 v34, v37, v34
	v_add_f32_e32 v37, 1.0, v36
	v_add_f32_e32 v39, -1.0, v38
	v_sub_f32_e32 v37, v35, v37
	v_sub_f32_e32 v35, v35, v39
	v_add_f32_e32 v37, v34, v37
	v_add_f32_e32 v34, v34, v35
	v_add_f32_e32 v43, v38, v34
	v_rcp_f32_e32 v45, v43
	v_sub_f32_e32 v35, v43, v38
	v_sub_f32_e32 v44, v34, v35
	v_add_f32_e32 v35, v36, v37
	v_mul_f32_e32 v47, v35, v45
	v_sub_f32_e32 v34, v35, v36
	v_mul_f32_e32 v36, v43, v47
	v_fma_f32 v38, v47, v43, -v36
	v_fmac_f32_e32 v38, v47, v44
	v_sub_f32_e32 v46, v37, v34
	v_add_f32_e32 v34, v36, v38
	v_sub_f32_e32 v37, v35, v34
	v_pk_add_f32 v[40:41], v[34:35], v[36:37] neg_lo:[0,1] neg_hi:[0,1]
	v_mov_b32_e32 v39, v34
	v_pk_add_f32 v[34:35], v[40:41], v[38:39] neg_lo:[0,1] neg_hi:[0,1]
	s_nop 0
	v_add_f32_e32 v35, v46, v35
	v_add_f32_e32 v34, v34, v35
	v_add_f32_e32 v35, v37, v34
	v_mul_f32_e32 v46, v45, v35
	v_mul_f32_e32 v36, v43, v46
	v_fma_f32 v38, v46, v43, -v36
	v_fmac_f32_e32 v38, v46, v44
	v_sub_f32_e32 v37, v37, v35
	v_add_f32_e32 v43, v34, v37
	v_add_f32_e32 v34, v36, v38
	v_sub_f32_e32 v37, v35, v34
	v_pk_add_f32 v[40:41], v[34:35], v[36:37] neg_lo:[0,1] neg_hi:[0,1]
	v_mov_b32_e32 v39, v34
	v_pk_add_f32 v[34:35], v[40:41], v[38:39] neg_lo:[0,1] neg_hi:[0,1]
	s_nop 0
	v_add_f32_e32 v35, v43, v35
	v_add_f32_e32 v34, v34, v35
	v_add_f32_e32 v35, v47, v46
	v_add_f32_e32 v34, v37, v34
	v_sub_f32_e32 v36, v35, v47
	v_mul_f32_e32 v34, v45, v34
	v_sub_f32_e32 v36, v46, v36
	v_add_f32_e32 v36, v36, v34
	v_add_f32_e32 v38, v35, v36
	v_mul_f32_e32 v39, v38, v38
	v_fmamk_f32 v34, v39, 0x3e9b6dac, v208
	v_fmaak_f32 v169, v39, v34, 0x3f2aaada
	v_cvt_f32_i32_e32 v34, v42
	v_sub_f32_e32 v35, v38, v35
	v_sub_f32_e32 v35, v36, v35
	v_ldexp_f32 v40, v35, 1
	v_mul_f32_e32 v35, v38, v39
	v_ldexp_f32 v37, v38, 1
	v_pk_mul_f32 v[38:39], v[34:35], v[168:169]
	s_nop 0
	v_fma_f32 v36, v34, s12, -v38
	v_fmac_f32_e32 v36, 0xb102e308, v34
	v_pk_add_f32 v[34:35], v[38:39], v[36:37]
	s_mov_b32 s12, 0x7f800000
	v_sub_f32_e32 v37, v35, v37
	v_sub_f32_e32 v37, v39, v37
	v_add_f32_e32 v41, v40, v37
	v_mov_b32_e32 v40, v38
	v_pk_add_f32 v[38:39], v[34:35], v[38:39] neg_lo:[0,1] neg_hi:[0,1]
	v_pk_add_f32 v[42:43], v[34:35], v[40:41]
	v_mov_b32_e32 v37, v34
	v_mov_b32_e32 v39, v43
	v_pk_add_f32 v[44:45], v[36:37], v[38:39] neg_lo:[0,1] neg_hi:[0,1]
	v_pk_add_f32 v[36:37], v[36:37], v[38:39]
	v_mov_b32_e32 v40, v41
	v_pk_add_f32 v[38:39], v[36:37], v[34:35] op_sel:[1,0] op_sel_hi:[0,1] neg_lo:[0,1] neg_hi:[0,1]
	s_nop 0
	v_pk_add_f32 v[46:47], v[42:43], v[38:39] op_sel_hi:[1,0] neg_lo:[0,1] neg_hi:[0,1]
	v_mov_b32_e32 v42, v43
	v_mov_b32_e32 v43, v37
	v_pk_mov_b32 v[38:39], v[34:35], v[38:39] op_sel:[1,0]
	v_mov_b32_e32 v41, v34
	v_pk_add_f32 v[38:39], v[42:43], v[38:39] neg_lo:[0,1] neg_hi:[0,1]
	v_mov_b32_e32 v46, v44
	v_pk_add_f32 v[34:35], v[40:41], v[38:39] neg_lo:[0,1] neg_hi:[0,1]
	v_mov_b32_e32 v45, v37
	v_pk_add_f32 v[38:39], v[46:47], v[34:35]
	v_cmp_neq_f32_e64 s[50:51], s12, v48
	v_pk_add_f32 v[40:41], v[38:39], v[38:39] op_sel:[0,1] op_sel_hi:[1,0]
	s_mov_b32 s12, 0x33800000
	v_pk_add_f32 v[36:37], v[36:37], v[40:41] op_sel:[1,0] op_sel_hi:[0,1]
	s_nop 0
	v_mov_b32_e32 v39, v36
	v_pk_add_f32 v[42:43], v[38:39], v[44:45] neg_lo:[0,1] neg_hi:[0,1]
	v_mov_b32_e32 v35, v40
	v_sub_f32_e32 v37, v38, v42
	v_pk_add_f32 v[34:35], v[34:35], v[42:43] neg_lo:[0,1] neg_hi:[0,1]
	v_sub_f32_e32 v37, v44, v37
	v_add_f32_e32 v34, v34, v37
	v_add_f32_e32 v34, v34, v35
	v_add_f32_e32 v34, v36, v34
	v_cndmask_b32_e64 v34, v212, v34, s[50:51]
	v_cmp_ngt_f32_e64 s[50:51], -1.0, v48
	s_nop 1
	v_cndmask_b32_e64 v34, v213, v34, s[50:51]
	v_cmp_neq_f32_e64 s[50:51], -1.0, v48
	s_nop 1
	v_cndmask_b32_e64 v34, v214, v34, s[50:51]
	v_cmp_lt_f32_e64 s[50:51], |v48|, s12
	s_nop 1
	v_cndmask_b32_e64 v34, v34, v48, s[50:51]
	v_sub_f32_e32 v34, v49, v34

; #define LAS __attribute__((address_space(3)))
; __device__ __forceinline__ unsigned cvt_pk_bf16(float lo, float hi) { unsigned r; asm volatile("v_cvt_pk_bf16_f32 %0, %1, %2" : "=v"(r) : "v"(lo), "v"(hi)); return r; }
; __device__ void phase0(const Params& P, LAS unsigned char* lds, const int G, const int bid) {
;     ...
;           for (int rr = 0; rr < 4; ++rr) { const int row = row0 + rr * G * 8; if (row >= NTOK) continue;
;               f32x4 (&v)[4] = vv[rr]; float ss = 0.f;
; #pragma unroll
;               for (int i = 0; i < 4; ++i)
; #pragma unroll
;                   for (int j = 0; j < 4; ++j) ss += v[i][j] * v[i][j];
; #pragma unroll
;               for (int o = 32; o >= 1; o >>= 1) ss += __shfl_xor(ss, o);
;               const float rstd = rsqrtf(ss * (1.0f / DM) + 1e-6f);
;               float ga[16];
; #pragma unroll
;               for (int c = 0; c < 16; ++c) ga[c] = 0.f;
; #pragma unroll
;               for (int i = 0; i < 4; ++i) { v[i] = v[i] * rstd * w4[i];
;                   u32x2 w; w.x = cvt_pk_bf16(v[i][0], v[i][1]); w.y = cvt_pk_bf16(v[i][2], v[i][3]);
;                   *(u32x2*)(abf + (size_t)row * DM + 4 * lane + 256 * i) = w;
; #pragma unroll
;                   for (int j = 0; j < 4; ++j) { const LAS float* wr_ = wg + (j * 256 + i * 64 + lane) * 20; const float a = v[i][j];
; #pragma unroll
;                       for (int q = 0; q < 4; ++q) { const f32x4 wv = *(const LAS f32x4*)(wr_ + 4 * q);
;                           ga[4 * q] += a * wv[0]; ga[4 * q + 1] += a * wv[1]; ga[4 * q + 2] += a * wv[2]; ga[4 * q + 3] += a * wv[3]; } } }
.LBB0_1060:
	s_or_b64 exec, exec, s[6:7]
	v_cmp_gt_i32_e64 s[50:51], s15, v84
	s_and_saveexec_b64 s[6:7], s[50:51]
	s_cbranch_execz .LBB0_1045
	s_waitcnt vmcnt(7)
	v_mul_f32_e32 v38, v31, v31
	v_fmac_f32_e32 v38, v30, v30
	v_fmac_f32_e32 v38, v32, v32
	v_fmac_f32_e32 v38, v33, v33
	s_waitcnt vmcnt(6)
	v_fmac_f32_e32 v38, v26, v26
	v_fmac_f32_e32 v38, v27, v27
	v_fmac_f32_e32 v38, v28, v28
	v_fmac_f32_e32 v38, v29, v29
	s_waitcnt vmcnt(5)
	v_fmac_f32_e32 v38, v22, v22
	v_fmac_f32_e32 v38, v23, v23
	v_fmac_f32_e32 v38, v24, v24
	v_fmac_f32_e32 v38, v25, v25
	s_waitcnt vmcnt(4)
	v_pk_mul_f32 v[36:37], v[18:19], v[18:19]
	s_waitcnt lgkmcnt(0)
	v_pk_mul_f32 v[34:35], v[20:21], v[20:21]
	v_add_f32_e32 v36, v36, v38
	v_add_f32_e32 v36, v37, v36
	v_add_f32_e32 v34, v34, v36
	v_add_f32_e32 v34, v35, v34
	ds_bpermute_b32 v35, v96, v34
	v_ashrrev_i32_e32 v85, 31, v84
	v_lshlrev_b64 v[36:37], 11, v[84:85]
	v_lshl_add_u64 v[36:37], v[80:81], 0, v[36:37]
	s_waitcnt lgkmcnt(0)
	v_add_f32_e32 v34, v34, v35
	ds_bpermute_b32 v35, v97, v34
	s_waitcnt lgkmcnt(0)
	v_add_f32_e32 v34, v34, v35
	ds_bpermute_b32 v35, v98, v34
	s_waitcnt lgkmcnt(0)
	v_add_f32_e32 v34, v34, v35
	ds_bpermute_b32 v35, v99, v34
	s_waitcnt lgkmcnt(0)
	v_add_f32_e32 v34, v34, v35
	ds_bpermute_b32 v35, v100, v34
	s_waitcnt lgkmcnt(0)
	v_add_f32_e32 v34, v34, v35
	ds_bpermute_b32 v35, v101, v34
	s_waitcnt lgkmcnt(0)
	v_add_f32_e32 v34, v34, v35
	v_fmamk_f32 v34, v34, 0x3a800000, v210
	v_cmp_gt_f32_e64 s[50:51], s30, v34
	v_mul_f32_e32 v35, 0x4b800000, v34
	s_nop 0
	v_cndmask_b32_e64 v34, v34, v35, s[50:51]
	v_rsq_f32_e32 v34, v34
	s_nop 0
	v_mul_f32_e32 v35, 0x45800000, v34
	v_cndmask_b32_e64 v34, v34, v35, s[50:51]
	v_pk_mul_f32 v[38:39], v[30:31], v[34:35] op_sel_hi:[1,0]
	v_pk_mul_f32 v[30:31], v[32:33], v[34:35] op_sel_hi:[1,0]
	v_pk_mul_f32 v[32:33], v[2:3], v[38:39]
	v_pk_mul_f32 v[30:31], v[4:5], v[30:31]
	v_cvt_pk_bf16_f32 v38, v32, v33
	s_nop 0
	v_cvt_pk_bf16_f32 v39, v30, v31
	global_store_dwordx2 v[36:37], v[38:39], off
	ds_read_b128 v[140:143], v102 offset:40960
	ds_read_b128 v[144:147], v102 offset:40976
	ds_read_b128 v[148:151], v102 offset:40992
	ds_read_b128 v[152:155], v102 offset:41008
	ds_read_b128 v[156:159], v102 offset:61440
	ds_read_b128 v[170:173], v102 offset:61456
	ds_read_b128 v[174:177], v102 offset:61472
	ds_read_b128 v[178:181], v102 offset:61488
	ds_read_b128 v[182:185], v103 offset:40960
	ds_read_b128 v[188:191], v103 offset:40976
	ds_read_b128 v[192:195], v103 offset:40992
	ds_read_b128 v[196:199], v103 offset:41008
	s_waitcnt lgkmcnt(11)
	v_fma_f32 v49, v140, v32, 0
	v_fma_f32 v46, v142, v32, 0
	s_waitcnt lgkmcnt(10)
	v_fma_f32 v42, v144, v32, 0
	v_fma_f32 v40, v145, v32, 0
	v_fma_f32 v38, v146, v32, 0
	v_fma_f32 v35, v147, v32, 0
	s_waitcnt lgkmcnt(9)
	v_fma_f32 v51, v148, v32, 0
	v_fma_f32 v50, v149, v32, 0
	ds_read_b128 v[222:225], v103 offset:61440
	v_fma_f32 v48, v141, v32, 0
	v_fma_f32 v43, v143, v32, 0
	v_fma_f32 v47, v150, v32, 0
	v_fma_f32 v45, v151, v32, 0
	s_waitcnt lgkmcnt(8)
	v_fmac_f32_e32 v49, v156, v33
	v_fmac_f32_e32 v48, v157, v33
	v_fmac_f32_e32 v46, v158, v33
	v_fmac_f32_e32 v43, v159, v33
	ds_read_b128 v[226:229], v103 offset:61456
	v_fma_f32 v44, v152, v32, 0
	v_fma_f32 v41, v153, v32, 0
	v_fma_f32 v39, v154, v32, 0
	v_fma_f32 v32, v155, v32, 0
	s_waitcnt lgkmcnt(8)
	v_fmac_f32_e32 v42, v170, v33
	v_fmac_f32_e32 v40, v171, v33
	v_fmac_f32_e32 v38, v172, v33
	v_fmac_f32_e32 v35, v173, v33
	ds_read_b128 v[230:233], v103 offset:61472
	s_waitcnt lgkmcnt(8)
	v_fmac_f32_e32 v51, v174, v33
	v_fmac_f32_e32 v50, v175, v33
	v_fmac_f32_e32 v47, v176, v33
	v_fmac_f32_e32 v45, v177, v33
	ds_read_b128 v[234:237], v103 offset:61488
	s_waitcnt lgkmcnt(8)
	v_fmac_f32_e32 v44, v178, v33
	v_fmac_f32_e32 v41, v179, v33
	v_fmac_f32_e32 v39, v180, v33
	v_fmac_f32_e32 v32, v181, v33
	ds_read_b128 v[144:147], v102 offset:46080
	ds_read_b128 v[140:143], v102 offset:46096
	ds_read_b128 v[148:151], v102 offset:46112
	ds_read_b128 v[156:159], v102 offset:46128
	s_waitcnt lgkmcnt(11)
	v_fmac_f32_e32 v49, v182, v30
	v_fmac_f32_e32 v48, v183, v30
	v_fmac_f32_e32 v46, v184, v30
	v_fmac_f32_e32 v43, v185, v30
	ds_read_b128 v[152:155], v103 offset:25600
	s_waitcnt lgkmcnt(11)
	v_fmac_f32_e32 v42, v30, v188
	v_fmac_f32_e32 v40, v30, v189
	v_fmac_f32_e32 v38, v30, v190
	v_fmac_f32_e32 v35, v30, v191
	s_waitcnt lgkmcnt(8)
	v_fmac_f32_e32 v49, v31, v222
	v_fmac_f32_e32 v48, v31, v223
	v_fmac_f32_e32 v46, v31, v224
	v_fmac_f32_e32 v43, v31, v225
	ds_read_b128 v[170:173], v103 offset:25616
	v_fmac_f32_e32 v51, v30, v192
	v_fmac_f32_e32 v50, v30, v193
	v_fmac_f32_e32 v47, v30, v194
	v_fmac_f32_e32 v45, v30, v195
	s_waitcnt lgkmcnt(8)
	v_fmac_f32_e32 v42, v31, v226
	v_fmac_f32_e32 v40, v31, v227
	v_fmac_f32_e32 v38, v31, v228
	v_fmac_f32_e32 v35, v31, v229
	ds_read_b128 v[174:177], v103 offset:25632
	v_fmac_f32_e32 v44, v30, v196
	v_fmac_f32_e32 v41, v30, v197
	v_fmac_f32_e32 v39, v30, v198
	v_fmac_f32_e32 v32, v30, v199
	s_waitcnt lgkmcnt(8)
	v_fmac_f32_e32 v51, v31, v230
	v_fmac_f32_e32 v50, v31, v231
	v_fmac_f32_e32 v47, v31, v232
	v_fmac_f32_e32 v45, v31, v233
	ds_read_b128 v[178:181], v103 offset:25648
	s_waitcnt lgkmcnt(8)
	v_fmac_f32_e32 v44, v31, v234
	v_fmac_f32_e32 v41, v31, v235
	v_fmac_f32_e32 v39, v31, v236
	v_fmac_f32_e32 v32, v31, v237
	v_pk_mul_f32 v[30:31], v[26:27], v[34:35] op_sel_hi:[1,0]
	v_pk_mul_f32 v[26:27], v[28:29], v[34:35] op_sel_hi:[1,0]
	v_pk_mul_f32 v[64:65], v[6:7], v[30:31]
	v_pk_mul_f32 v[26:27], v[8:9], v[26:27]
	v_cvt_pk_bf16_f32 v28, v64, v65
	s_nop 0
	v_cvt_pk_bf16_f32 v29, v26, v27
	global_store_dwordx2 v[36:37], v[28:29], off offset:512
	ds_read_b128 v[182:185], v103 offset:46080
	ds_read_b128 v[188:191], v103 offset:46096
	ds_read_b128 v[222:225], v103 offset:46112
	ds_read_b128 v[192:195], v103 offset:46128
	s_waitcnt lgkmcnt(11)
; #define LAS __attribute__((address_space(3)))
; __device__ __forceinline__ unsigned cvt_pk_bf16(float lo, float hi) { unsigned r; asm volatile("v_cvt_pk_bf16_f32 %0, %1, %2" : "=v"(r) : "v"(lo), "v"(hi)); return r; }
; __device__ void phase0(const Params& P, LAS unsigned char* lds, const int G, const int bid) {
;     ...
;               for (int i = 0; i < 4; ++i) { v[i] = v[i] * rstd * w4[i];
;                   u32x2 w; w.x = cvt_pk_bf16(v[i][0], v[i][1]); w.y = cvt_pk_bf16(v[i][2], v[i][3]);
;                   *(u32x2*)(abf + (size_t)row * DM + 4 * lane + 256 * i) = w;
; #pragma unroll
;                   for (int j = 0; j < 4; ++j) { const LAS float* wr_ = wg + (j * 256 + i * 64 + lane) * 20; const float a = v[i][j];
; #pragma unroll
;                       for (int q = 0; q < 4; ++q) { const f32x4 wv = *(const LAS f32x4*)(wr_ + 4 * q);
;                           ga[4 * q] += a * wv[0]; ga[4 * q + 1] += a * wv[1]; ga[4 * q + 2] += a * wv[2]; ga[4 * q + 3] += a * wv[3]; } } }
	v_fmac_f32_e32 v49, v64, v144
	v_fmac_f32_e32 v48, v64, v145
	v_fmac_f32_e32 v46, v64, v146
	v_fmac_f32_e32 v43, v64, v147
	s_waitcnt lgkmcnt(10)
	v_fmac_f32_e32 v42, v64, v140
	v_fmac_f32_e32 v40, v64, v141
	v_fmac_f32_e32 v38, v64, v142
	v_fmac_f32_e32 v35, v64, v143
	s_waitcnt lgkmcnt(9)
	v_fmac_f32_e32 v51, v64, v148
	v_fmac_f32_e32 v50, v64, v149
	v_fmac_f32_e32 v47, v64, v150
	v_fmac_f32_e32 v45, v64, v151
	s_waitcnt lgkmcnt(8)
	v_fmac_f32_e32 v44, v64, v156
	v_fmac_f32_e32 v41, v64, v157
	v_fmac_f32_e32 v39, v64, v158
	v_fmac_f32_e32 v32, v64, v159
	ds_read_b128 v[226:229], v104
	ds_read_b128 v[196:199], v105
	ds_read_b128 v[230:233], v106
	ds_read_b128 v[234:237], v107
	s_waitcnt lgkmcnt(11)
	v_fmac_f32_e32 v49, v65, v152
	v_fmac_f32_e32 v48, v65, v153
	v_fmac_f32_e32 v46, v65, v154
	v_fmac_f32_e32 v43, v65, v155
	ds_read_b128 v[144:147], v102 offset:51200
	s_waitcnt lgkmcnt(11)
	v_fmac_f32_e32 v42, v65, v170
	v_fmac_f32_e32 v40, v65, v171
	v_fmac_f32_e32 v38, v65, v172
	v_fmac_f32_e32 v35, v65, v173
	s_waitcnt lgkmcnt(8)
	v_fmac_f32_e32 v49, v26, v182
	v_fmac_f32_e32 v48, v26, v183
	v_fmac_f32_e32 v46, v26, v184
	v_fmac_f32_e32 v43, v26, v185
	ds_read_b128 v[140:143], v102 offset:51216
	v_fmac_f32_e32 v51, v65, v174
	v_fmac_f32_e32 v50, v65, v175
	v_fmac_f32_e32 v47, v65, v176
	v_fmac_f32_e32 v45, v65, v177
	s_waitcnt lgkmcnt(8)
	v_fmac_f32_e32 v42, v26, v188
	v_fmac_f32_e32 v40, v26, v189
	v_fmac_f32_e32 v38, v26, v190
	v_fmac_f32_e32 v35, v26, v191
	ds_read_b128 v[148:151], v102 offset:51232
	v_fmac_f32_e32 v44, v65, v178
	v_fmac_f32_e32 v41, v65, v179
	v_fmac_f32_e32 v39, v65, v180
	v_fmac_f32_e32 v32, v65, v181
	s_waitcnt lgkmcnt(8)
	v_fmac_f32_e32 v51, v26, v222
	v_fmac_f32_e32 v50, v26, v223
	v_fmac_f32_e32 v47, v26, v224
	v_fmac_f32_e32 v45, v26, v225
	ds_read_b128 v[156:159], v102 offset:51248
	s_waitcnt lgkmcnt(8)
	v_fmac_f32_e32 v44, v26, v192
	v_fmac_f32_e32 v41, v26, v193
	v_fmac_f32_e32 v39, v26, v194
	v_fmac_f32_e32 v32, v26, v195
	ds_read_b128 v[152:155], v103 offset:30720
	s_waitcnt lgkmcnt(8)
	v_fmac_f32_e32 v49, v27, v226
	v_fmac_f32_e32 v48, v27, v227
	v_fmac_f32_e32 v46, v27, v228
	v_fmac_f32_e32 v43, v27, v229
	ds_read_b128 v[170:173], v103 offset:30736
	s_waitcnt lgkmcnt(8)
	v_fmac_f32_e32 v42, v27, v196
	v_fmac_f32_e32 v40, v27, v197
	v_fmac_f32_e32 v38, v27, v198
	v_fmac_f32_e32 v35, v27, v199
	ds_read_b128 v[182:185], v103 offset:30752
	s_waitcnt lgkmcnt(8)
	v_fmac_f32_e32 v51, v27, v230
	v_fmac_f32_e32 v50, v27, v231
	v_fmac_f32_e32 v47, v27, v232
	v_fmac_f32_e32 v45, v27, v233
	ds_read_b128 v[174:177], v103 offset:30768
	s_waitcnt lgkmcnt(8)
	v_fmac_f32_e32 v44, v27, v234
	v_fmac_f32_e32 v41, v27, v235
	v_fmac_f32_e32 v39, v27, v236
	v_fmac_f32_e32 v32, v27, v237
	v_pk_mul_f32 v[26:27], v[22:23], v[34:35] op_sel_hi:[1,0]
	v_pk_mul_f32 v[22:23], v[24:25], v[34:35] op_sel_hi:[1,0]
	v_pk_mul_f32 v[60:61], v[10:11], v[26:27]
	v_pk_mul_f32 v[22:23], v[12:13], v[22:23]
	v_cvt_pk_bf16_f32 v24, v60, v61
	s_nop 0
	v_cvt_pk_bf16_f32 v25, v22, v23
	global_store_dwordx2 v[36:37], v[24:25], off offset:1024
	ds_read_b128 v[188:191], v103 offset:51200
	ds_read_b128 v[178:181], v103 offset:51216
	ds_read_b128 v[222:225], v103 offset:51232
	ds_read_b128 v[192:195], v103 offset:51248
	s_waitcnt lgkmcnt(11)
	v_fmac_f32_e32 v49, v60, v144
	v_fmac_f32_e32 v48, v60, v145
	v_fmac_f32_e32 v46, v60, v146
	v_fmac_f32_e32 v43, v60, v147
	s_waitcnt lgkmcnt(10)
	v_fmac_f32_e32 v42, v60, v140
	v_fmac_f32_e32 v40, v60, v141
	v_fmac_f32_e32 v38, v60, v142
	v_fmac_f32_e32 v35, v60, v143
	s_waitcnt lgkmcnt(9)
	v_fmac_f32_e32 v51, v60, v148
	v_fmac_f32_e32 v50, v60, v149
	v_fmac_f32_e32 v47, v60, v150
	v_fmac_f32_e32 v45, v60, v151
	s_waitcnt lgkmcnt(8)
	v_fmac_f32_e32 v44, v60, v156
	v_fmac_f32_e32 v41, v60, v157
	v_fmac_f32_e32 v39, v60, v158
	v_fmac_f32_e32 v32, v60, v159
	ds_read_b128 v[226:229], v108
	ds_read_b128 v[196:199], v109
	ds_read_b128 v[230:233], v110
	ds_read_b128 v[234:237], v111
	s_waitcnt lgkmcnt(11)
	v_fmac_f32_e32 v49, v61, v152
	v_fmac_f32_e32 v48, v61, v153
	v_fmac_f32_e32 v46, v61, v154
	v_fmac_f32_e32 v43, v61, v155
	ds_read_b128 v[144:147], v102 offset:56320
	s_waitcnt lgkmcnt(11)
	v_fmac_f32_e32 v42, v61, v170
	v_fmac_f32_e32 v40, v61, v171
	v_fmac_f32_e32 v38, v61, v172
	v_fmac_f32_e32 v35, v61, v173
	s_waitcnt lgkmcnt(8)
	v_fmac_f32_e32 v49, v22, v188
	v_fmac_f32_e32 v48, v22, v189
	v_fmac_f32_e32 v46, v22, v190
	v_fmac_f32_e32 v43, v22, v191
	ds_read_b128 v[140:143], v102 offset:56336
	v_fmac_f32_e32 v51, v61, v182
	v_fmac_f32_e32 v50, v61, v183
	v_fmac_f32_e32 v47, v61, v184
	v_fmac_f32_e32 v45, v61, v185
	s_waitcnt lgkmcnt(8)
	v_fmac_f32_e32 v42, v22, v178
	v_fmac_f32_e32 v40, v22, v179
	v_fmac_f32_e32 v38, v22, v180
	v_fmac_f32_e32 v35, v22, v181
	ds_read_b128 v[148:151], v102 offset:56352
	v_fmac_f32_e32 v44, v61, v174
	v_fmac_f32_e32 v41, v61, v175
	v_fmac_f32_e32 v39, v61, v176
	v_fmac_f32_e32 v32, v61, v177
	s_waitcnt lgkmcnt(8)
	v_fmac_f32_e32 v51, v22, v222
	v_fmac_f32_e32 v50, v22, v223
	v_fmac_f32_e32 v47, v22, v224
	v_fmac_f32_e32 v45, v22, v225
	ds_read_b128 v[156:159], v102 offset:56368
	s_waitcnt lgkmcnt(8)
	v_fmac_f32_e32 v44, v22, v192
	v_fmac_f32_e32 v41, v22, v193
	v_fmac_f32_e32 v39, v22, v194
	v_fmac_f32_e32 v32, v22, v195
	ds_read_b128 v[152:155], v103 offset:35840
	s_waitcnt lgkmcnt(8)
	v_fmac_f32_e32 v49, v23, v226
	v_fmac_f32_e32 v48, v23, v227
	v_fmac_f32_e32 v46, v23, v228
	v_fmac_f32_e32 v43, v23, v229
	ds_read_b128 v[170:173], v103 offset:35856
	s_waitcnt lgkmcnt(8)
	v_fmac_f32_e32 v42, v23, v196
	v_fmac_f32_e32 v40, v23, v197
	v_fmac_f32_e32 v38, v23, v198
	v_fmac_f32_e32 v35, v23, v199
	ds_read_b128 v[188:191], v103 offset:35872
	s_waitcnt lgkmcnt(8)
; #define LAS __attribute__((address_space(3)))
; __device__ void phase0(const Params& P, LAS unsigned char* lds, const int G, const int bid) {
;     ...
;                   for (int j = 0; j < 4; ++j) { const LAS float* wr_ = wg + (j * 256 + i * 64 + lane) * 20; const float a = v[i][j];
; #pragma unroll
;                       for (int q = 0; q < 4; ++q) { const f32x4 wv = *(const LAS f32x4*)(wr_ + 4 * q);
;                           ga[4 * q] += a * wv[0]; ga[4 * q + 1] += a * wv[1]; ga[4 * q + 2] += a * wv[2]; ga[4 * q + 3] += a * wv[3]; } } }
;               float r8[8], r4[4], r2[2], r1;
; #pragma unroll
;               for (int c = 0; c < 8; ++c) { const bool hi = (lane & 32) != 0; const float send = hi ? ga[c] : ga[c + 8], keep = hi ? ga[c + 8] : ga[c]; r8[c] = keep + __shfl_xor(send, 32); }
; #pragma unroll
;               for (int c = 0; c < 4; ++c) { const bool hi = (lane & 16) != 0; const float send = hi ? r8[c] : r8[c + 4], keep = hi ? r8[c + 4] : r8[c]; r4[c] = keep + __shfl_xor(send, 16); }
; #pragma unroll
;               for (int c = 0; c < 2; ++c) { const bool hi = (lane & 8) != 0; const float send = hi ? r4[c] : r4[c + 2], keep = hi ? r4[c + 2] : r4[c]; r2[c] = keep + __shfl_xor(send, 8); }
;               { const bool hi = (lane & 4) != 0; const float send = hi ? r2[0] : r2[1], keep = hi ? r2[1] : r2[0]; r1 = keep + __shfl_xor(send, 4); }
;               r1 += __shfl_xor(r1, 2); r1 += __shfl_xor(r1, 1);
	v_fmac_f32_e32 v51, v23, v230
	v_fmac_f32_e32 v50, v23, v231
	v_fmac_f32_e32 v47, v23, v232
	v_fmac_f32_e32 v45, v23, v233
	ds_read_b128 v[182:185], v103 offset:35888
	s_waitcnt lgkmcnt(8)
	v_fmac_f32_e32 v44, v23, v234
	v_fmac_f32_e32 v41, v23, v235
	v_fmac_f32_e32 v39, v23, v236
	v_fmac_f32_e32 v32, v23, v237
	v_pk_mul_f32 v[22:23], v[18:19], v[34:35] op_sel_hi:[1,0]
	v_pk_mul_f32 v[18:19], v[20:21], v[34:35] op_sel_hi:[1,0]
	v_pk_mul_f32 v[56:57], v[14:15], v[22:23]
	v_pk_mul_f32 v[18:19], v[16:17], v[18:19]
	v_cvt_pk_bf16_f32 v20, v56, v57
	s_nop 0
	v_cvt_pk_bf16_f32 v21, v18, v19
	global_store_dwordx2 v[36:37], v[20:21], off offset:1536
	ds_read_b128 v[178:181], v103 offset:56320
	ds_read_b128 v[174:177], v103 offset:56336
	ds_read_b128 v[222:225], v103 offset:56352
	ds_read_b128 v[192:195], v103 offset:56368
	s_waitcnt lgkmcnt(11)
	v_fmac_f32_e32 v49, v56, v144
	v_fmac_f32_e32 v48, v56, v145
	v_fmac_f32_e32 v46, v56, v146
	v_fmac_f32_e32 v43, v56, v147
	s_waitcnt lgkmcnt(10)
	v_fmac_f32_e32 v42, v56, v140
	v_fmac_f32_e32 v40, v56, v141
	v_fmac_f32_e32 v38, v56, v142
	v_fmac_f32_e32 v35, v56, v143
	s_waitcnt lgkmcnt(9)
	v_fmac_f32_e32 v51, v56, v148
	v_fmac_f32_e32 v50, v56, v149
	v_fmac_f32_e32 v47, v56, v150
	v_fmac_f32_e32 v45, v56, v151
	s_waitcnt lgkmcnt(8)
	v_fmac_f32_e32 v44, v56, v156
	v_fmac_f32_e32 v41, v56, v157
	v_fmac_f32_e32 v39, v56, v158
	v_fmac_f32_e32 v32, v56, v159
	ds_read_b128 v[226:229], v112
	ds_read_b128 v[196:199], v113
	ds_read_b128 v[230:233], v114
	ds_read_b128 v[234:237], v115
	s_waitcnt lgkmcnt(11)
	v_fmac_f32_e32 v49, v57, v152
	v_fmac_f32_e32 v48, v57, v153
	v_fmac_f32_e32 v46, v57, v154
	v_fmac_f32_e32 v43, v57, v155
	s_waitcnt lgkmcnt(10)
	v_fmac_f32_e32 v42, v57, v170
	v_fmac_f32_e32 v40, v57, v171
	v_fmac_f32_e32 v38, v57, v172
	v_fmac_f32_e32 v35, v57, v173
	s_waitcnt lgkmcnt(7)
	v_fmac_f32_e32 v49, v18, v178
	v_fmac_f32_e32 v48, v18, v179
	v_fmac_f32_e32 v46, v18, v180
	v_fmac_f32_e32 v43, v18, v181
	v_fmac_f32_e32 v51, v57, v188
	v_fmac_f32_e32 v50, v57, v189
	v_fmac_f32_e32 v47, v57, v190
	v_fmac_f32_e32 v45, v57, v191
	s_waitcnt lgkmcnt(6)
	v_fmac_f32_e32 v42, v18, v174
	v_fmac_f32_e32 v40, v18, v175
	v_fmac_f32_e32 v38, v18, v176
	v_fmac_f32_e32 v35, v18, v177
	v_fmac_f32_e32 v44, v57, v182
	v_fmac_f32_e32 v41, v57, v183
	v_fmac_f32_e32 v39, v57, v184
	v_fmac_f32_e32 v32, v57, v185
	s_waitcnt lgkmcnt(5)
	v_fmac_f32_e32 v51, v18, v222
	v_fmac_f32_e32 v50, v18, v223
	v_fmac_f32_e32 v47, v18, v224
	v_fmac_f32_e32 v45, v18, v225
	s_waitcnt lgkmcnt(4)
	v_fmac_f32_e32 v44, v18, v192
	v_fmac_f32_e32 v41, v18, v193
	v_fmac_f32_e32 v39, v18, v194
	v_fmac_f32_e32 v32, v18, v195
	s_waitcnt lgkmcnt(3)
	v_fmac_f32_e32 v49, v19, v226
	v_fmac_f32_e32 v48, v19, v227
	v_fmac_f32_e32 v46, v19, v228
	v_fmac_f32_e32 v43, v19, v229
	s_waitcnt lgkmcnt(2)
	v_fmac_f32_e32 v42, v19, v196
	v_fmac_f32_e32 v40, v19, v197
	v_fmac_f32_e32 v38, v19, v198
	v_fmac_f32_e32 v35, v19, v199
	s_waitcnt lgkmcnt(1)
	v_fmac_f32_e32 v51, v19, v230
	v_fmac_f32_e32 v50, v19, v231
	v_fmac_f32_e32 v47, v19, v232
	v_fmac_f32_e32 v45, v19, v233
	v_cndmask_b32_e32 v18, v49, v51, vcc
	ds_bpermute_b32 v18, v96, v18
	s_waitcnt lgkmcnt(1)
	v_fmac_f32_e32 v44, v19, v234
	v_fmac_f32_e32 v41, v19, v235
	v_fmac_f32_e32 v39, v19, v236
	v_fmac_f32_e32 v32, v19, v237
	v_cndmask_b32_e32 v19, v51, v49, vcc
	s_waitcnt lgkmcnt(0)
	v_add_f32_e32 v18, v19, v18
	v_cndmask_b32_e32 v19, v48, v50, vcc
	ds_bpermute_b32 v19, v96, v19
	v_cndmask_b32_e32 v20, v50, v48, vcc
	v_cndmask_b32_e32 v21, v47, v46, vcc
	v_cndmask_b32_e32 v22, v45, v43, vcc
	v_cndmask_b32_e32 v23, v44, v42, vcc
	s_waitcnt lgkmcnt(0)
	v_add_f32_e32 v19, v20, v19
	v_cndmask_b32_e32 v20, v46, v47, vcc
	ds_bpermute_b32 v20, v96, v20
	v_cndmask_b32_e32 v24, v41, v40, vcc
	v_cndmask_b32_e32 v25, v39, v38, vcc
	v_cndmask_b32_e32 v26, v32, v35, vcc
	s_waitcnt lgkmcnt(0)
	v_add_f32_e32 v20, v21, v20
	v_cndmask_b32_e32 v21, v43, v45, vcc
	ds_bpermute_b32 v21, v96, v21
	s_waitcnt lgkmcnt(0)
	v_add_f32_e32 v21, v22, v21
	v_cndmask_b32_e32 v22, v42, v44, vcc
	ds_bpermute_b32 v22, v96, v22
	s_waitcnt lgkmcnt(0)
	v_add_f32_e32 v22, v23, v22
	v_cndmask_b32_e32 v23, v40, v41, vcc
	ds_bpermute_b32 v23, v96, v23
	s_waitcnt lgkmcnt(0)
	v_add_f32_e32 v23, v24, v23
	v_cndmask_b32_e32 v24, v38, v39, vcc
	ds_bpermute_b32 v24, v96, v24
	s_waitcnt lgkmcnt(0)
	v_add_f32_e32 v24, v25, v24
	v_cndmask_b32_e32 v25, v35, v32, vcc
	ds_bpermute_b32 v25, v96, v25
	s_waitcnt lgkmcnt(0)
	v_add_f32_e32 v25, v26, v25
	v_cndmask_b32_e64 v26, v18, v22, s[42:43]
	v_cndmask_b32_e64 v18, v22, v18, s[42:43]
	ds_bpermute_b32 v22, v97, v26
	s_waitcnt lgkmcnt(0)
	v_add_f32_e32 v18, v18, v22
	v_cndmask_b32_e64 v22, v19, v23, s[42:43]
	ds_bpermute_b32 v22, v97, v22
	v_cndmask_b32_e64 v19, v23, v19, s[42:43]
	s_waitcnt lgkmcnt(0)
	v_add_f32_e32 v19, v19, v22
	v_cndmask_b32_e64 v22, v20, v24, s[42:43]
	ds_bpermute_b32 v22, v97, v22
	v_cndmask_b32_e64 v20, v24, v20, s[42:43]
	s_waitcnt lgkmcnt(0)
	v_add_f32_e32 v20, v20, v22
	v_cndmask_b32_e64 v22, v21, v25, s[42:43]
	ds_bpermute_b32 v22, v97, v22
	v_cndmask_b32_e64 v21, v25, v21, s[42:43]
	s_waitcnt lgkmcnt(0)
	v_add_f32_e32 v21, v21, v22
	v_cndmask_b32_e64 v22, v18, v20, s[44:45]
	v_cndmask_b32_e64 v18, v20, v18, s[44:45]
	ds_bpermute_b32 v20, v98, v22
	s_waitcnt lgkmcnt(0)
	v_add_f32_e32 v18, v18, v20
	v_cndmask_b32_e64 v20, v19, v21, s[44:45]
	ds_bpermute_b32 v20, v98, v20
	v_cndmask_b32_e64 v19, v21, v19, s[44:45]
	s_waitcnt lgkmcnt(0)
	v_add_f32_e32 v19, v19, v20
	v_cndmask_b32_e64 v20, v18, v19, s[46:47]
	v_cndmask_b32_e64 v18, v19, v18, s[46:47]
	ds_bpermute_b32 v19, v99, v20
	s_waitcnt lgkmcnt(0)
	v_add_f32_e32 v18, v18, v19
	ds_bpermute_b32 v19, v100, v18
	s_waitcnt lgkmcnt(0)
	v_add_f32_e32 v18, v18, v19
	ds_bpermute_b32 v19, v101, v18
	s_and_b64 exec, exec, s[48:49]
	s_cbranch_execz .LBB0_1045
; __device__ __forceinline__ float logsigmoidf_(float x) { return fminf(x, 0.0f) - log1pf(__expf(-fabsf(x))); }
; __device__ void phase0(const Params& P, LAS unsigned char* lds, const int G, const int bid) {
;     ...
;               if ((lane & 3) == 0) { float gv = r1 + gbias; if (gcol >= 8) gv = logsigmoidf_(gv); gates[(size_t)row * 16 + gcol] = gv; }
	s_waitcnt lgkmcnt(0)
	v_add_f32_e32 v18, v18, v19
	v_add_f32_e32 v18, v91, v18
	s_and_saveexec_b64 s[8:9], s[40:41]
	s_cbranch_execz .LBB0_1044
	s_mov_b32 s12, 0xbfb8aa3b
	v_mul_f32_e64 v19, |v18|, s12
	v_exp_f32_e32 v32, v19
	v_max_f32_e32 v18, v18, v18
	v_min_f32_e32 v33, 0, v18
	s_mov_b32 s12, 0x3f2aaaab
	v_add_f32_e32 v20, 1.0, v32
	v_add_f32_e32 v18, -1.0, v20
	v_sub_f32_e32 v19, v18, v20
	v_sub_f32_e32 v18, v32, v18
	v_add_f32_e32 v19, 1.0, v19
	v_add_f32_e32 v21, v18, v19
	v_frexp_mant_f32_e32 v22, v20
	v_cvt_f64_f32_e32 v[18:19], v20
	v_frexp_exp_i32_f64_e32 v18, v[18:19]
	v_cmp_gt_f32_e64 s[50:51], s12, v22
	s_mov_b32 s12, 0x3f317218
	s_nop 0
	v_subbrev_co_u32_e64 v26, s[50:51], 0, v18, s[50:51]
	v_sub_u32_e32 v18, 0, v26
	v_ldexp_f32 v19, v20, v18
	v_add_f32_e32 v20, -1.0, v19
	v_add_f32_e32 v22, 1.0, v19
	v_ldexp_f32 v18, v21, v18
	v_add_f32_e32 v21, 1.0, v20
	v_add_f32_e32 v23, -1.0, v22
	v_sub_f32_e32 v21, v19, v21
	v_sub_f32_e32 v19, v19, v23
	v_add_f32_e32 v21, v18, v21
	v_add_f32_e32 v18, v18, v19
	v_add_f32_e32 v27, v22, v18
	v_rcp_f32_e32 v29, v27
	v_sub_f32_e32 v19, v27, v22
	v_sub_f32_e32 v28, v18, v19
	v_add_f32_e32 v19, v20, v21
	v_mul_f32_e32 v31, v19, v29
	v_sub_f32_e32 v18, v19, v20
	v_mul_f32_e32 v20, v27, v31
	v_fma_f32 v22, v31, v27, -v20
	v_fmac_f32_e32 v22, v31, v28
	v_sub_f32_e32 v30, v21, v18
	v_add_f32_e32 v18, v20, v22
	v_sub_f32_e32 v21, v19, v18
	v_pk_add_f32 v[24:25], v[18:19], v[20:21] neg_lo:[0,1] neg_hi:[0,1]
	v_mov_b32_e32 v23, v18
	v_pk_add_f32 v[18:19], v[24:25], v[22:23] neg_lo:[0,1] neg_hi:[0,1]
	s_nop 0
	v_add_f32_e32 v19, v30, v19
	v_add_f32_e32 v18, v18, v19
	v_add_f32_e32 v19, v21, v18
	v_mul_f32_e32 v30, v29, v19
	v_mul_f32_e32 v20, v27, v30
	v_fma_f32 v22, v30, v27, -v20
	v_fmac_f32_e32 v22, v30, v28
	v_sub_f32_e32 v21, v21, v19
	v_add_f32_e32 v27, v18, v21
	v_add_f32_e32 v18, v20, v22
	v_sub_f32_e32 v21, v19, v18
	v_pk_add_f32 v[24:25], v[18:19], v[20:21] neg_lo:[0,1] neg_hi:[0,1]
	v_mov_b32_e32 v23, v18
	v_pk_add_f32 v[18:19], v[24:25], v[22:23] neg_lo:[0,1] neg_hi:[0,1]
	s_nop 0
	v_add_f32_e32 v19, v27, v19
	v_add_f32_e32 v18, v18, v19
	v_add_f32_e32 v19, v31, v30
	v_add_f32_e32 v18, v21, v18
	v_sub_f32_e32 v20, v19, v31
	v_mul_f32_e32 v18, v29, v18
	v_sub_f32_e32 v20, v30, v20
	v_add_f32_e32 v20, v20, v18
	v_add_f32_e32 v22, v19, v20
	v_mul_f32_e32 v23, v22, v22
	v_fmamk_f32 v18, v23, 0x3e9b6dac, v208
	v_fmaak_f32 v169, v23, v18, 0x3f2aaada
	v_cvt_f32_i32_e32 v18, v26
	v_sub_f32_e32 v19, v22, v19
	v_sub_f32_e32 v19, v20, v19
	v_ldexp_f32 v24, v19, 1
	v_mul_f32_e32 v19, v22, v23
	v_ldexp_f32 v21, v22, 1
	v_pk_mul_f32 v[22:23], v[18:19], v[168:169]
	s_nop 0
	v_fma_f32 v20, v18, s12, -v22
	v_fmac_f32_e32 v20, 0xb102e308, v18
	v_pk_add_f32 v[18:19], v[22:23], v[20:21]
	s_mov_b32 s12, 0x7f800000
	v_sub_f32_e32 v21, v19, v21
	v_sub_f32_e32 v21, v23, v21
	v_add_f32_e32 v25, v24, v21
	v_mov_b32_e32 v24, v22
	v_pk_add_f32 v[22:23], v[18:19], v[22:23] neg_lo:[0,1] neg_hi:[0,1]
	v_pk_add_f32 v[26:27], v[18:19], v[24:25]
	v_mov_b32_e32 v21, v18
	v_mov_b32_e32 v23, v27
	v_pk_add_f32 v[28:29], v[20:21], v[22:23] neg_lo:[0,1] neg_hi:[0,1]
	v_pk_add_f32 v[20:21], v[20:21], v[22:23]
	v_mov_b32_e32 v24, v25
	v_pk_add_f32 v[22:23], v[20:21], v[18:19] op_sel:[1,0] op_sel_hi:[0,1] neg_lo:[0,1] neg_hi:[0,1]
	s_nop 0
	v_pk_add_f32 v[30:31], v[26:27], v[22:23] op_sel_hi:[1,0] neg_lo:[0,1] neg_hi:[0,1]
	v_mov_b32_e32 v26, v27
	v_mov_b32_e32 v27, v21
	v_pk_mov_b32 v[22:23], v[18:19], v[22:23] op_sel:[1,0]
	v_mov_b32_e32 v25, v18
	v_pk_add_f32 v[22:23], v[26:27], v[22:23] neg_lo:[0,1] neg_hi:[0,1]
	v_mov_b32_e32 v30, v28
	v_pk_add_f32 v[18:19], v[24:25], v[22:23] neg_lo:[0,1] neg_hi:[0,1]
	v_mov_b32_e32 v29, v21
	v_pk_add_f32 v[22:23], v[30:31], v[18:19]
	v_cmp_neq_f32_e64 s[50:51], s12, v32
	v_pk_add_f32 v[24:25], v[22:23], v[22:23] op_sel:[0,1] op_sel_hi:[1,0]
	s_mov_b32 s12, 0x33800000
	v_pk_add_f32 v[20:21], v[20:21], v[24:25] op_sel:[1,0] op_sel_hi:[0,1]
	s_nop 0
	v_mov_b32_e32 v23, v20
	v_pk_add_f32 v[26:27], v[22:23], v[28:29] neg_lo:[0,1] neg_hi:[0,1]
	v_mov_b32_e32 v19, v24
	v_sub_f32_e32 v21, v22, v26
	v_pk_add_f32 v[18:19], v[18:19], v[26:27] neg_lo:[0,1] neg_hi:[0,1]
	v_sub_f32_e32 v21, v28, v21
	v_add_f32_e32 v18, v18, v21
	v_add_f32_e32 v18, v18, v19
	v_add_f32_e32 v18, v20, v18
	v_cndmask_b32_e64 v18, v212, v18, s[50:51]
	v_cmp_ngt_f32_e64 s[50:51], -1.0, v32
	s_nop 1
	v_cndmask_b32_e64 v18, v213, v18, s[50:51]
	v_cmp_neq_f32_e64 s[50:51], -1.0, v32
	s_nop 1
	v_cndmask_b32_e64 v18, v214, v18, s[50:51]
	v_cmp_lt_f32_e64 s[50:51], |v32|, s12
	s_nop 1
	v_cndmask_b32_e64 v18, v18, v32, s[50:51]
	v_sub_f32_e32 v18, v33, v18
	s_branch .LBB0_1044
